# up-GEMM epilogue: weight load issued at loop exit, LDS broadcast staged right after the rstd scaling so its latency hides behind the raw-row stores
# speedup vs baseline: 1.0080x; 1.0033x over previous
; #define PG8_STAGE(bufoff, gbase, voff) do { _Pragma("unroll") for (int _i = 0; _i < 2; ++_i) \
;         __builtin_amdgcn_global_load_lds((const unsigned*)((const char*)(gbase) + (voff)[_i]), (LAS unsigned*)(lds + (bufoff) + ldsw + _i * 8192), 16, 0, 0); } while (0)
; #define PG8_LDA(dst, b, h) do { _Pragma("unroll") for (int m = 0; m < 4; ++m) _Pragma("unroll") for (int k = 0; k < 2; ++k) dst[m][k] = *(const LAS bf16x8*)(lds + PG8_SA(b, h) + aoff + m * 2048 + k * 1024); } while (0)
; #define PG8_LDB(dst, b, h) do { _Pragma("unroll") for (int n = 0; n < 2; ++n) _Pragma("unroll") for (int k = 0; k < 2; ++k) dst[n][k] = *(const LAS bf16x8*)(lds + PG8_SB(b, h) + boff + n * 2048 + k * 1024); } while (0)
; #define PG8_MMA(ai, bj, At, Bt) do { __builtin_amdgcn_s_setprio(1); _Pragma("unroll") for (int m = 0; m < 4; ++m) _Pragma("unroll") for (int n = 0; n < 2; ++n) _Pragma("unroll") for (int k = 0; k < 2; ++k) \
;         acc[ai][bj][m][n] = __builtin_amdgcn_mfma_f32_16x16x32_bf16(Bt[n][k], At[m][k], acc[ai][bj][m][n], 0, 0, 0); __builtin_amdgcn_s_setprio(0); } while (0)
; #define PG8_WAIT_V(n) asm volatile("s_waitcnt vmcnt(" #n ")" ::: "memory")
; #define PG8_WAIT_L(n) asm volatile("s_waitcnt lgkmcnt(" #n ")" ::: "memory")
; #define PG8_BAR __builtin_amdgcn_s_barrier()
; #define PG8_SCHED __builtin_amdgcn_sched_barrier(0)
; template <class Epi, bool KREV = false>
; __device__ __forceinline__ void gemm_phase(LAS unsigned char* lds, const Gemm g, const StaticOrder& S, const Epi& E, int wave_s) {
;     ...
;         for (int t = 0; t < nt; t += 2) {
;             const bool last = (t == nt - 2);
;             const char* a1 = cA + (size_t)(t + 1) * kstep;
;             const char* a2 = last ? nA : cA + (size_t)(t + 2) * kstep; const char* b2 = last ? nB : cB + (size_t)(t + 2) * kstep;
;             const char* a3 = a2 + kstep; const char* b3 = b2 + kstep;
;             PG8_LDB(B0, 0, 0); PG8_LDB(B1, 0, 1); PG8_SCHED; PG8_LDA(At, 0, 0); PG8_STAGE(PG8_SA(1, 1), a1 + hstep, voffA);
;             PG8_WAIT_V(8); PG8_WAIT_L(0); PG8_BAR; PG8_MMA(0, 0, At, B0); PG8_MMA(0, 1, At, B1); PG8_BAR; PG8_SCHED;
;             PG8_LDA(At, 0, 1); PG8_STAGE(PG8_SB(0, 0), b2, voffB); PG8_STAGE(PG8_SB(0, 1), b2 + bh, voffB); PG8_STAGE(PG8_SA(0, 0), a2, voffA);
;             PG8_WAIT_V(8); PG8_WAIT_L(0); PG8_BAR; PG8_MMA(1, 0, At, B0); PG8_MMA(1, 1, At, B1); PG8_BAR; PG8_SCHED;
.Lsb2:
.LBB0_836:
	v_add_u32_e32 v154, 0x10000, v135
	v_add_u32_e32 v170, 0x14000, v135
	ds_read_b128 v[142:145], v154
	ds_read_b128 v[146:149], v154 offset:1024
	ds_read_b128 v[150:153], v154 offset:2048
	ds_read_b128 v[154:157], v154 offset:3072
	ds_read_b128 v[158:161], v170
	ds_read_b128 v[162:165], v170 offset:1024
	ds_read_b128 v[166:169], v170 offset:2048
	ds_read_b128 v[170:173], v170 offset:3072
	ds_read_b128 v[178:181], v194
	ds_read_b128 v[182:185], v194 offset:1024
	ds_read_b128 v[186:189], v194 offset:2048
	ds_read_b128 v[196:199], v194 offset:3072
	ds_read_b128 v[200:203], v194 offset:4096
	ds_read_b128 v[204:207], v194 offset:5120
	ds_read_b128 v[218:221], v194 offset:6144
	ds_read_b128 v[222:225], v194 offset:7168
	s_add_u32 s56, s54, 0xfff80080
	s_addc_u32 s57, s55, -1
	s_add_i32 s84, 0, 0x10000
	s_cmp_eq_u32 s83, 28
	s_cselect_b32 s59, s73, s57
	s_cselect_b32 s58, s74, s56
	s_cselect_b32 s57, s75, s82
	s_cselect_b32 s56, s77, s80
	s_add_i32 s86, 0, 0x14000
	s_add_i32 m0, s19, 0xc000
	s_nop 0
	global_load_lds_dwordx4 v138, s[54:55]
	s_add_i32 m0, s19, 0xe000
	s_nop 0
	global_load_lds_dwordx4 v140, s[54:55]
	s_waitcnt vmcnt(8)
	s_waitcnt lgkmcnt(0)
	s_barrier
	s_setprio 1
	s_waitcnt lgkmcnt(0)
	v_mfma_f32_16x16x32_bf16 v[124:127], v[142:145], v[178:181], v[124:127]
	v_mfma_f32_16x16x32_bf16 v[120:123], v[150:153], v[178:181], v[120:123]
	v_mfma_f32_16x16x32_bf16 v[68:71], v[142:145], v[186:189], v[68:71]
	v_mfma_f32_16x16x32_bf16 v[64:67], v[150:153], v[186:189], v[64:67]
	v_mfma_f32_16x16x32_bf16 v[60:63], v[142:145], v[200:203], v[60:63]
	v_mfma_f32_16x16x32_bf16 v[20:23], v[150:153], v[200:203], v[20:23]
	v_mfma_f32_16x16x32_bf16 v[108:111], v[142:145], v[218:221], v[108:111]
	v_mfma_f32_16x16x32_bf16 v[104:107], v[150:153], v[218:221], v[104:107]
	v_mfma_f32_16x16x32_bf16 v[124:127], v[146:149], v[182:185], v[124:127]
	v_mfma_f32_16x16x32_bf16 v[120:123], v[154:157], v[182:185], v[120:123]
	v_mfma_f32_16x16x32_bf16 v[68:71], v[146:149], v[196:199], v[68:71]
	v_mfma_f32_16x16x32_bf16 v[64:67], v[154:157], v[196:199], v[64:67]
	v_mfma_f32_16x16x32_bf16 v[60:63], v[146:149], v[204:207], v[60:63]
	v_mfma_f32_16x16x32_bf16 v[20:23], v[154:157], v[204:207], v[20:23]
	v_mfma_f32_16x16x32_bf16 v[108:111], v[146:149], v[222:225], v[108:111]
	v_mfma_f32_16x16x32_bf16 v[104:107], v[154:157], v[222:225], v[104:107]
	s_setprio 0
	s_setprio 1
	v_mfma_f32_16x16x32_bf16 v[116:119], v[158:161], v[178:181], v[116:119]
	v_mfma_f32_16x16x32_bf16 v[112:115], v[166:169], v[178:181], v[112:115]
	v_mfma_f32_16x16x32_bf16 v[52:55], v[158:161], v[186:189], v[52:55]
	v_mfma_f32_16x16x32_bf16 v[48:51], v[166:169], v[186:189], v[48:51]
	v_mfma_f32_16x16x32_bf16 v[44:47], v[158:161], v[200:203], v[44:47]
	v_mfma_f32_16x16x32_bf16 v[16:19], v[166:169], v[200:203], v[16:19]
	v_mfma_f32_16x16x32_bf16 v[100:103], v[158:161], v[218:221], v[100:103]
	v_mfma_f32_16x16x32_bf16 v[96:99], v[166:169], v[218:221], v[96:99]
	v_mfma_f32_16x16x32_bf16 v[116:119], v[162:165], v[182:185], v[116:119]
	v_mfma_f32_16x16x32_bf16 v[112:115], v[170:173], v[182:185], v[112:115]
	v_mfma_f32_16x16x32_bf16 v[52:55], v[162:165], v[196:199], v[52:55]
	v_mfma_f32_16x16x32_bf16 v[48:51], v[170:173], v[196:199], v[48:51]
	v_mfma_f32_16x16x32_bf16 v[44:47], v[162:165], v[204:207], v[44:47]
	v_mfma_f32_16x16x32_bf16 v[16:19], v[170:173], v[204:207], v[16:19]
	v_mfma_f32_16x16x32_bf16 v[100:103], v[162:165], v[222:225], v[100:103]
	s_barrier
	v_mfma_f32_16x16x32_bf16 v[96:99], v[170:173], v[222:225], v[96:99]
	s_setprio 0
	s_add_u32 s98, s56, s2
	s_addc_u32 s99, s57, s3
	s_add_u32 s100, s58, s2
	s_addc_u32 s101, s59, s3
	s_add_i32 s84, s84, s66
	s_mov_b32 m0, s84
	ds_read_b128 v[178:181], v194 offset:16384
	ds_read_b128 v[182:185], v194 offset:17408
	ds_read_b128 v[186:189], v194 offset:18432
	ds_read_b128 v[196:199], v194 offset:19456
	ds_read_b128 v[200:203], v194 offset:20480
	ds_read_b128 v[204:207], v194 offset:21504
	ds_read_b128 v[218:221], v194 offset:22528
	ds_read_b128 v[222:225], v194 offset:23552
	global_load_lds_dwordx4 v176, s[56:57]
	s_add_i32 m0, s84, 0x2000
	s_add_u32 s84, s56, 0x1600000
	s_addc_u32 s85, s57, 0
	s_add_i32 s86, s86, s66
	global_load_lds_dwordx4 v132, s[56:57]
	s_mov_b32 m0, s86
	s_nop 0
	global_load_lds_dwordx4 v176, s[84:85]
	s_add_i32 m0, s86, 0x2000
	s_nop 0
	global_load_lds_dwordx4 v132, s[84:85]
	s_mov_b32 m0, s19
	s_nop 0
	global_load_lds_dwordx4 v128, s[58:59]
	s_mov_b32 m0, s21
	s_nop 0
	global_load_lds_dwordx4 v130, s[58:59]
	s_waitcnt vmcnt(8)
	s_waitcnt lgkmcnt(0)
	s_barrier
; #define PG8_STAGE(bufoff, gbase, voff) do { _Pragma("unroll") for (int _i = 0; _i < 2; ++_i) \
;         __builtin_amdgcn_global_load_lds((const unsigned*)((const char*)(gbase) + (voff)[_i]), (LAS unsigned*)(lds + (bufoff) + ldsw + _i * 8192), 16, 0, 0); } while (0)
; #define PG8_LDA(dst, b, h) do { _Pragma("unroll") for (int m = 0; m < 4; ++m) _Pragma("unroll") for (int k = 0; k < 2; ++k) dst[m][k] = *(const LAS bf16x8*)(lds + PG8_SA(b, h) + aoff + m * 2048 + k * 1024); } while (0)
; #define PG8_LDB(dst, b, h) do { _Pragma("unroll") for (int n = 0; n < 2; ++n) _Pragma("unroll") for (int k = 0; k < 2; ++k) dst[n][k] = *(const LAS bf16x8*)(lds + PG8_SB(b, h) + boff + n * 2048 + k * 1024); } while (0)
; #define PG8_MMA(ai, bj, At, Bt) do { __builtin_amdgcn_s_setprio(1); _Pragma("unroll") for (int m = 0; m < 4; ++m) _Pragma("unroll") for (int n = 0; n < 2; ++n) _Pragma("unroll") for (int k = 0; k < 2; ++k) \
;         acc[ai][bj][m][n] = __builtin_amdgcn_mfma_f32_16x16x32_bf16(Bt[n][k], At[m][k], acc[ai][bj][m][n], 0, 0, 0); __builtin_amdgcn_s_setprio(0); } while (0)
; #define PG8_WAIT_V(n) asm volatile("s_waitcnt vmcnt(" #n ")" ::: "memory")
; #define PG8_WAIT_L(n) asm volatile("s_waitcnt lgkmcnt(" #n ")" ::: "memory")
; #define PG8_BAR __builtin_amdgcn_s_barrier()
; #define PG8_SCHED __builtin_amdgcn_sched_barrier(0)
; template <class Epi, bool KREV = false>
; __device__ __forceinline__ void gemm_phase(LAS unsigned char* lds, const Gemm g, const StaticOrder& S, const Epi& E, int wave_s) {
;     ...
;             PG8_WAIT_V(8); PG8_WAIT_L(0); PG8_BAR; PG8_MMA(1, 0, At, B0); PG8_MMA(1, 1, At, B1); PG8_BAR; PG8_SCHED;
;             PG8_LDB(B0, 1, 0); PG8_LDB(B1, 1, 1); PG8_SCHED; PG8_LDA(At, 1, 0); PG8_STAGE(PG8_SA(0, 1), a2 + hstep, voffA);
;             PG8_WAIT_V(8); PG8_WAIT_L(0); PG8_BAR; PG8_MMA(0, 0, At, B0); PG8_MMA(0, 1, At, B1); PG8_BAR; PG8_SCHED;
	s_setprio 1
	s_waitcnt lgkmcnt(0)
	v_mfma_f32_16x16x32_bf16 v[92:95], v[142:145], v[178:181], v[92:95]
	v_mfma_f32_16x16x32_bf16 v[88:91], v[150:153], v[178:181], v[88:91]
	v_mfma_f32_16x16x32_bf16 v[36:39], v[142:145], v[186:189], v[36:39]
	v_mfma_f32_16x16x32_bf16 v[12:15], v[150:153], v[186:189], v[12:15]
	v_mfma_f32_16x16x32_bf16 v[32:35], v[142:145], v[200:203], v[32:35]
	v_mfma_f32_16x16x32_bf16 v[4:7], v[150:153], v[200:203], v[4:7]
	v_mfma_f32_16x16x32_bf16 v[76:79], v[142:145], v[218:221], v[76:79]
	v_mfma_f32_16x16x32_bf16 v[56:59], v[150:153], v[218:221], v[56:59]
	v_mfma_f32_16x16x32_bf16 v[92:95], v[146:149], v[182:185], v[92:95]
	v_mfma_f32_16x16x32_bf16 v[88:91], v[154:157], v[182:185], v[88:91]
	v_mfma_f32_16x16x32_bf16 v[36:39], v[146:149], v[196:199], v[36:39]
	v_mfma_f32_16x16x32_bf16 v[12:15], v[154:157], v[196:199], v[12:15]
	v_mfma_f32_16x16x32_bf16 v[32:35], v[146:149], v[204:207], v[32:35]
	v_mfma_f32_16x16x32_bf16 v[4:7], v[154:157], v[204:207], v[4:7]
	v_mfma_f32_16x16x32_bf16 v[76:79], v[146:149], v[222:225], v[76:79]
	v_mfma_f32_16x16x32_bf16 v[56:59], v[154:157], v[222:225], v[56:59]
	s_setprio 0
	s_setprio 1
	v_mfma_f32_16x16x32_bf16 v[84:87], v[158:161], v[178:181], v[84:87]
	v_mfma_f32_16x16x32_bf16 v[80:83], v[166:169], v[178:181], v[80:83]
	v_mfma_f32_16x16x32_bf16 v[28:31], v[158:161], v[186:189], v[28:31]
	v_mfma_f32_16x16x32_bf16 v[8:11], v[166:169], v[186:189], v[8:11]
	v_mfma_f32_16x16x32_bf16 v[24:27], v[158:161], v[200:203], v[24:27]
	v_mfma_f32_16x16x32_bf16 v[0:3], v[166:169], v[200:203], v[0:3]
	v_mfma_f32_16x16x32_bf16 v[72:75], v[158:161], v[218:221], v[72:75]
	v_mfma_f32_16x16x32_bf16 v[40:43], v[166:169], v[218:221], v[40:43]
	v_mfma_f32_16x16x32_bf16 v[84:87], v[162:165], v[182:185], v[84:87]
	v_mfma_f32_16x16x32_bf16 v[80:83], v[170:173], v[182:185], v[80:83]
	v_mfma_f32_16x16x32_bf16 v[28:31], v[162:165], v[196:199], v[28:31]
	v_mfma_f32_16x16x32_bf16 v[8:11], v[170:173], v[196:199], v[8:11]
	v_mfma_f32_16x16x32_bf16 v[24:27], v[162:165], v[204:207], v[24:27]
	v_mfma_f32_16x16x32_bf16 v[0:3], v[170:173], v[204:207], v[0:3]
	v_mfma_f32_16x16x32_bf16 v[72:75], v[162:165], v[222:225], v[72:75]
	s_barrier
	v_mfma_f32_16x16x32_bf16 v[40:43], v[170:173], v[222:225], v[40:43]
	s_setprio 0
	s_add_i32 s84, 0, 0x18000
	s_add_i32 s85, 0, 0x1c000
	v_add_u32_e32 v154, s84, v135
	v_add_u32_e32 v170, s85, v135
	ds_read_b128 v[142:145], v154
	ds_read_b128 v[146:149], v154 offset:1024
	ds_read_b128 v[150:153], v154 offset:2048
	ds_read_b128 v[154:157], v154 offset:3072
	ds_read_b128 v[158:161], v170
	ds_read_b128 v[162:165], v170 offset:1024
	ds_read_b128 v[166:169], v170 offset:2048
	ds_read_b128 v[170:173], v170 offset:3072
	s_add_u32 s58, s58, 0x80000
	s_addc_u32 s59, s59, 0
	s_mov_b32 m0, s67
	ds_read_b128 v[178:181], v194 offset:32768
	ds_read_b128 v[182:185], v194 offset:33792
	ds_read_b128 v[186:189], v194 offset:34816
	ds_read_b128 v[196:199], v194 offset:35840
	ds_read_b128 v[200:203], v194 offset:36864
	ds_read_b128 v[204:207], v194 offset:37888
	ds_read_b128 v[218:221], v194 offset:38912
	ds_read_b128 v[222:225], v194 offset:39936
	global_load_lds_dwordx4 v128, s[58:59]
	s_mov_b32 m0, s68
	s_nop 0
	global_load_lds_dwordx4 v130, s[58:59]
	s_waitcnt vmcnt(8)
	s_waitcnt lgkmcnt(0)
	s_barrier
	s_setprio 1
	s_waitcnt lgkmcnt(0)
	v_mfma_f32_16x16x32_bf16 v[124:127], v[142:145], v[178:181], v[124:127]
	v_mfma_f32_16x16x32_bf16 v[120:123], v[150:153], v[178:181], v[120:123]
	v_mfma_f32_16x16x32_bf16 v[68:71], v[142:145], v[186:189], v[68:71]
	v_mfma_f32_16x16x32_bf16 v[64:67], v[150:153], v[186:189], v[64:67]
	v_mfma_f32_16x16x32_bf16 v[60:63], v[142:145], v[200:203], v[60:63]
	v_mfma_f32_16x16x32_bf16 v[20:23], v[150:153], v[200:203], v[20:23]
	v_mfma_f32_16x16x32_bf16 v[108:111], v[142:145], v[218:221], v[108:111]
	v_mfma_f32_16x16x32_bf16 v[104:107], v[150:153], v[218:221], v[104:107]
	v_mfma_f32_16x16x32_bf16 v[124:127], v[146:149], v[182:185], v[124:127]
	v_mfma_f32_16x16x32_bf16 v[120:123], v[154:157], v[182:185], v[120:123]
	v_mfma_f32_16x16x32_bf16 v[68:71], v[146:149], v[196:199], v[68:71]
	v_mfma_f32_16x16x32_bf16 v[64:67], v[154:157], v[196:199], v[64:67]
	v_mfma_f32_16x16x32_bf16 v[60:63], v[146:149], v[204:207], v[60:63]
	v_mfma_f32_16x16x32_bf16 v[20:23], v[154:157], v[204:207], v[20:23]
	v_mfma_f32_16x16x32_bf16 v[108:111], v[146:149], v[222:225], v[108:111]
	v_mfma_f32_16x16x32_bf16 v[104:107], v[154:157], v[222:225], v[104:107]
	s_setprio 0
	s_setprio 1
	v_mfma_f32_16x16x32_bf16 v[116:119], v[158:161], v[178:181], v[116:119]
	v_mfma_f32_16x16x32_bf16 v[112:115], v[166:169], v[178:181], v[112:115]
	v_mfma_f32_16x16x32_bf16 v[52:55], v[158:161], v[186:189], v[52:55]
	v_mfma_f32_16x16x32_bf16 v[48:51], v[166:169], v[186:189], v[48:51]
	v_mfma_f32_16x16x32_bf16 v[44:47], v[158:161], v[200:203], v[44:47]
	v_mfma_f32_16x16x32_bf16 v[16:19], v[166:169], v[200:203], v[16:19]
	v_mfma_f32_16x16x32_bf16 v[100:103], v[158:161], v[218:221], v[100:103]
	v_mfma_f32_16x16x32_bf16 v[96:99], v[166:169], v[218:221], v[96:99]
	v_mfma_f32_16x16x32_bf16 v[116:119], v[162:165], v[182:185], v[116:119]
	v_mfma_f32_16x16x32_bf16 v[112:115], v[170:173], v[182:185], v[112:115]
	v_mfma_f32_16x16x32_bf16 v[52:55], v[162:165], v[196:199], v[52:55]
	v_mfma_f32_16x16x32_bf16 v[48:51], v[170:173], v[196:199], v[48:51]
	v_mfma_f32_16x16x32_bf16 v[44:47], v[162:165], v[204:207], v[44:47]
	v_mfma_f32_16x16x32_bf16 v[16:19], v[170:173], v[204:207], v[16:19]
	v_mfma_f32_16x16x32_bf16 v[100:103], v[162:165], v[222:225], v[100:103]
	s_barrier
;     __device__ __forceinline__ void operator()(f32x4 (&acc)[2][2][4][2], const Unit& u, int wr, int wc, int fr, int fq, const LAS float* rtab) const {
;         const int c0 = u.pn * 128 + wc * 32 + 8 * fq;
; #pragma unroll
;         for (int ai = 0; ai < 2; ++ai)
; #pragma unroll
;             for (int m = 0; m < 4; ++m) { const float r = rtab[ai * HALF + wr * 64 + m * 16 + fr];
; #pragma unroll
;                 for (int bj = 0; bj < 2; ++bj)
; #pragma unroll
;                     for (int n = 0; n < 2; ++n) acc[ai][bj][m][n] = acc[ai][bj][m][n] * r; }
; #pragma unroll
;         for (int ai = 0; ai < 2; ++ai) {
;             const int blk = (u.pm * BM + ai * HALF + wr * 64) >> 6;
;             if (fr < 2) { bf16_t* rp = raw + ((size_t)blk * 4 + fr) * UP_N + c0;
;                 const f32x4 g0 = acc[ai][0][0][0], g1 = acc[ai][0][0][1], u0 = acc[ai][1][0][0], u1 = acc[ai][1][0][1];
;                 u32x4 w; w.x = cvt_pk_bf16(g0[0], g0[1]); w.y = cvt_pk_bf16(g0[2], g0[3]); w.z = cvt_pk_bf16(g1[0], g1[1]); w.w = cvt_pk_bf16(g1[2], g1[3]); *(u32x4*)rp = w;
;                 w.x = cvt_pk_bf16(u0[0], u0[1]); w.y = cvt_pk_bf16(u0[2], u0[3]); w.z = cvt_pk_bf16(u1[0], u1[1]); w.w = cvt_pk_bf16(u1[2], u1[3]); *(u32x4*)(rp + DFF) = w; }
;             if (fr >= 14) { bf16_t* rp = raw + ((size_t)blk * 4 + (fr - 12)) * UP_N + c0;
;                 const f32x4 g0 = acc[ai][0][3][0], g1 = acc[ai][0][3][1], u0 = acc[ai][1][3][0], u1 = acc[ai][1][3][1];
;                 u32x4 w; w.x = cvt_pk_bf16(g0[0], g0[1]); w.y = cvt_pk_bf16(g0[2], g0[3]); w.z = cvt_pk_bf16(g1[0], g1[1]); w.w = cvt_pk_bf16(g1[2], g1[3]); *(u32x4*)rp = w;
;                 w.x = cvt_pk_bf16(u0[0], u0[1]); w.y = cvt_pk_bf16(u0[2], u0[3]); w.z = cvt_pk_bf16(u1[0], u1[1]); w.w = cvt_pk_bf16(u1[2], u1[3]); *(u32x4*)(rp + DFF) = w; }
;         }
;         u32x2 ypk[2][4];
; #pragma unroll
;         for (int n = 0; n < 2; ++n) {
; template <class Epi, bool KREV = false>
; __device__ __forceinline__ void gemm_phase(LAS unsigned char* lds, const Gemm g, const StaticOrder& S, const Epi& E, int wave_s) {
;     ...
;             PG8_LDA(At, 1, 1); PG8_STAGE(PG8_SB(1, 0), b3, voffB); PG8_STAGE(PG8_SB(1, 1), b3 + bh, voffB); PG8_STAGE(PG8_SA(1, 0), a3, voffA);
;             PG8_WAIT_V(8); PG8_WAIT_L(0); PG8_BAR; PG8_MMA(1, 0, At, B0); PG8_MMA(1, 1, At, B1); PG8_BAR; PG8_SCHED;
;         }
;         if (wr == 0) PG8_BAR;
	v_mfma_f32_16x16x32_bf16 v[96:99], v[170:173], v[222:225], v[96:99]
	s_setprio 0
	s_add_i32 s58, s84, s66
	s_mov_b32 m0, s58
	ds_read_b128 v[178:181], v194 offset:49152
	ds_read_b128 v[182:185], v194 offset:50176
	ds_read_b128 v[186:189], v194 offset:51200
	ds_read_b128 v[196:199], v194 offset:52224
	ds_read_b128 v[200:203], v194 offset:53248
	ds_read_b128 v[204:207], v194 offset:54272
	ds_read_b128 v[218:221], v194 offset:55296
	ds_read_b128 v[222:225], v194 offset:56320
	global_load_lds_dwordx4 v176, s[98:99]
	s_add_i32 m0, s58, 0x2000
	s_add_u32 s56, s56, 0x1600080
	s_addc_u32 s57, s57, 0
	s_add_i32 s58, s85, s66
	global_load_lds_dwordx4 v132, s[98:99]
	s_mov_b32 m0, s58
	s_nop 0
	global_load_lds_dwordx4 v176, s[56:57]
	s_add_i32 m0, s58, 0x2000
	s_nop 0
	global_load_lds_dwordx4 v132, s[56:57]
	s_mov_b32 m0, s70
	s_nop 0
	global_load_lds_dwordx4 v128, s[100:101]
	s_mov_b32 m0, s71
	s_nop 0
	global_load_lds_dwordx4 v130, s[100:101]
	s_waitcnt vmcnt(8)
	s_waitcnt lgkmcnt(0)
	s_barrier
	s_setprio 1
	s_waitcnt lgkmcnt(0)
	v_mfma_f32_16x16x32_bf16 v[92:95], v[142:145], v[178:181], v[92:95]
	v_mfma_f32_16x16x32_bf16 v[88:91], v[150:153], v[178:181], v[88:91]
	v_mfma_f32_16x16x32_bf16 v[36:39], v[142:145], v[186:189], v[36:39]
	v_mfma_f32_16x16x32_bf16 v[12:15], v[150:153], v[186:189], v[12:15]
	v_mfma_f32_16x16x32_bf16 v[32:35], v[142:145], v[200:203], v[32:35]
	v_mfma_f32_16x16x32_bf16 v[4:7], v[150:153], v[200:203], v[4:7]
	v_mfma_f32_16x16x32_bf16 v[76:79], v[142:145], v[218:221], v[76:79]
	v_mfma_f32_16x16x32_bf16 v[56:59], v[150:153], v[218:221], v[56:59]
	v_mfma_f32_16x16x32_bf16 v[92:95], v[146:149], v[182:185], v[92:95]
	v_mfma_f32_16x16x32_bf16 v[88:91], v[154:157], v[182:185], v[88:91]
	v_mfma_f32_16x16x32_bf16 v[36:39], v[146:149], v[196:199], v[36:39]
	v_mfma_f32_16x16x32_bf16 v[12:15], v[154:157], v[196:199], v[12:15]
	v_mfma_f32_16x16x32_bf16 v[32:35], v[146:149], v[204:207], v[32:35]
	v_mfma_f32_16x16x32_bf16 v[4:7], v[154:157], v[204:207], v[4:7]
	v_mfma_f32_16x16x32_bf16 v[76:79], v[146:149], v[222:225], v[76:79]
	v_mfma_f32_16x16x32_bf16 v[56:59], v[154:157], v[222:225], v[56:59]
	s_setprio 0
	s_setprio 1
	v_mfma_f32_16x16x32_bf16 v[84:87], v[158:161], v[178:181], v[84:87]
	v_mfma_f32_16x16x32_bf16 v[80:83], v[166:169], v[178:181], v[80:83]
	v_mfma_f32_16x16x32_bf16 v[28:31], v[158:161], v[186:189], v[28:31]
	v_mfma_f32_16x16x32_bf16 v[8:11], v[166:169], v[186:189], v[8:11]
	v_mfma_f32_16x16x32_bf16 v[24:27], v[158:161], v[200:203], v[24:27]
	v_mfma_f32_16x16x32_bf16 v[0:3], v[166:169], v[200:203], v[0:3]
	v_mfma_f32_16x16x32_bf16 v[72:75], v[158:161], v[218:221], v[72:75]
	v_mfma_f32_16x16x32_bf16 v[40:43], v[166:169], v[218:221], v[40:43]
	v_mfma_f32_16x16x32_bf16 v[84:87], v[162:165], v[182:185], v[84:87]
	v_mfma_f32_16x16x32_bf16 v[80:83], v[170:173], v[182:185], v[80:83]
	v_mfma_f32_16x16x32_bf16 v[28:31], v[162:165], v[196:199], v[28:31]
	v_mfma_f32_16x16x32_bf16 v[8:11], v[170:173], v[196:199], v[8:11]
	s_add_i32 s83, s83, 2
	s_add_u32 s54, s54, 0x100
	s_addc_u32 s55, s55, 0
	v_mfma_f32_16x16x32_bf16 v[24:27], v[162:165], v[204:207], v[24:27]
	s_add_u32 s80, s80, 0x100
	s_addc_u32 s82, s82, 0
	v_mfma_f32_16x16x32_bf16 v[0:3], v[170:173], v[204:207], v[0:3]
	s_cmp_gt_u32 s83, 29
	v_mfma_f32_16x16x32_bf16 v[72:75], v[162:165], v[222:225], v[72:75]
	s_barrier
	v_mfma_f32_16x16x32_bf16 v[40:43], v[170:173], v[222:225], v[40:43]
	s_setprio 0
	s_cbranch_scc0 .LBB0_836
	v_lshl_add_u32 v252, s1, 10, v192
	v_mad_u32_u24 v252, v134, 12, v252
	ds_read_b128 v[228:231], v252
	ds_read_b128 v[232:235], v252 offset:512
	v_lshl_or_b32 v213, s0, 7, v193
	v_lshlrev_b32_e32 v253, 2, v213
	v_and_b32_e32 v217, 63, v208
	v_lshrrev_b32_e32 v142, 1, v134
	v_and_b32_e32 v143, 1, v134
	v_and_b32_e32 v178, 3, v142
	v_cmp_eq_u32_e64 s[56:57], 3, v178
	v_cmp_lt_u32_e64 s[54:55], 3, v142
	v_mul_u32_u24_e32 v210, 0xb000, v178
	v_mov_b32_e32 v211, 0
	v_cndmask_b32_e64 v210, v210, 0, s[56:57]
	v_lshl_add_u32 v210, v143, 4, v210
	v_lshl_add_u32 v210, v213, 2, v210
	v_add_u32_e32 v179, 0x5800, v210
	v_cndmask_b32_e64 v210, v210, v179, s[54:55]
	v_mov_b32_e32 v218, s34
	v_mov_b32_e32 v219, s35
	v_mov_b32_e32 v252, s36
	v_mov_b32_e32 v253, s37
	v_cndmask_b32_e64 v218, v218, v252, s[56:57]
	v_cndmask_b32_e64 v219, v219, v253, s[56:57]
	v_lshl_add_u64 v[210:211], v[218:219], 0, v[210:211]
	global_load_dwordx4 v[224:227], v[210:211], off
	v_lshl_add_u32 v195, v217, 4, s19
	v_and_b32_e32 v212, 0x30, v217
	v_lshl_add_u32 v212, v212, 4, s19
	s_and_b64 vcc, exec, s[38:39]
	s_cbranch_vccz .LBB0_839
	s_barrier
;     __device__ __forceinline__ void operator()(f32x4 (&acc)[2][2][4][2], const Unit& u, int wr, int wc, int fr, int fq, const LAS float* rtab) const {
;         const int c0 = u.pn * 128 + wc * 32 + 8 * fq;
; #pragma unroll
;         for (int ai = 0; ai < 2; ++ai)
; #pragma unroll
;             for (int m = 0; m < 4; ++m) { const float r = rtab[ai * HALF + wr * 64 + m * 16 + fr];
; #pragma unroll
;                 for (int bj = 0; bj < 2; ++bj)
; #pragma unroll
;                     for (int n = 0; n < 2; ++n) acc[ai][bj][m][n] = acc[ai][bj][m][n] * r; }
;     ...
;             const f32x4 wg0 = *(const f32x4*)(cw + cn), wg1 = *(const f32x4*)(cw + UP_N + cn), wg2 = *(const f32x4*)(cw + 2 * UP_N + cn), bg = *(const f32x4*)(cb + cn);
;             const f32x4 wu0 = *(const f32x4*)(cw + DFF + cn), wu1 = *(const f32x4*)(cw + UP_N + DFF + cn), wu2 = *(const f32x4*)(cw + 2 * UP_N + DFF + cn), bu = *(const f32x4*)(cb + DFF + cn);
.LBB0_839:
	s_waitcnt lgkmcnt(0)
	v_pk_mul_f32 v[124:125], v[124:125], v[228:229] op_sel_hi:[1,0]
	v_pk_mul_f32 v[126:127], v[126:127], v[228:229] op_sel_hi:[1,0]
	v_pk_mul_f32 v[120:121], v[120:121], v[228:229] op_sel_hi:[1,0]
	v_pk_mul_f32 v[122:123], v[122:123], v[228:229] op_sel_hi:[1,0]
	v_pk_mul_f32 v[116:117], v[116:117], v[228:229] op_sel_hi:[1,0]
	v_pk_mul_f32 v[118:119], v[118:119], v[228:229] op_sel_hi:[1,0]
	v_pk_mul_f32 v[112:113], v[112:113], v[228:229] op_sel_hi:[1,0]
	v_pk_mul_f32 v[114:115], v[114:115], v[228:229] op_sel_hi:[1,0]
	v_pk_mul_f32 v[68:69], v[68:69], v[228:229] op_sel:[0,1] op_sel_hi:[1,1]
	v_pk_mul_f32 v[70:71], v[70:71], v[228:229] op_sel:[0,1] op_sel_hi:[1,1]
	v_pk_mul_f32 v[64:65], v[64:65], v[228:229] op_sel:[0,1] op_sel_hi:[1,1]
	v_pk_mul_f32 v[66:67], v[66:67], v[228:229] op_sel:[0,1] op_sel_hi:[1,1]
	v_pk_mul_f32 v[52:53], v[52:53], v[228:229] op_sel:[0,1] op_sel_hi:[1,1]
	v_pk_mul_f32 v[54:55], v[54:55], v[228:229] op_sel:[0,1] op_sel_hi:[1,1]
	v_pk_mul_f32 v[48:49], v[48:49], v[228:229] op_sel:[0,1] op_sel_hi:[1,1]
	v_pk_mul_f32 v[50:51], v[50:51], v[228:229] op_sel:[0,1] op_sel_hi:[1,1]
	v_pk_mul_f32 v[60:61], v[60:61], v[230:231] op_sel_hi:[1,0]
	v_pk_mul_f32 v[62:63], v[62:63], v[230:231] op_sel_hi:[1,0]
	v_pk_mul_f32 v[20:21], v[20:21], v[230:231] op_sel_hi:[1,0]
	v_pk_mul_f32 v[22:23], v[22:23], v[230:231] op_sel_hi:[1,0]
	v_pk_mul_f32 v[44:45], v[44:45], v[230:231] op_sel_hi:[1,0]
	v_pk_mul_f32 v[46:47], v[46:47], v[230:231] op_sel_hi:[1,0]
	v_pk_mul_f32 v[16:17], v[16:17], v[230:231] op_sel_hi:[1,0]
	v_pk_mul_f32 v[18:19], v[18:19], v[230:231] op_sel_hi:[1,0]
	v_pk_mul_f32 v[108:109], v[108:109], v[230:231] op_sel:[0,1] op_sel_hi:[1,1]
	v_pk_mul_f32 v[110:111], v[110:111], v[230:231] op_sel:[0,1] op_sel_hi:[1,1]
	v_pk_mul_f32 v[104:105], v[104:105], v[230:231] op_sel:[0,1] op_sel_hi:[1,1]
	v_pk_mul_f32 v[106:107], v[106:107], v[230:231] op_sel:[0,1] op_sel_hi:[1,1]
	v_pk_mul_f32 v[100:101], v[100:101], v[230:231] op_sel:[0,1] op_sel_hi:[1,1]
	v_pk_mul_f32 v[102:103], v[102:103], v[230:231] op_sel:[0,1] op_sel_hi:[1,1]
	v_pk_mul_f32 v[96:97], v[96:97], v[230:231] op_sel:[0,1] op_sel_hi:[1,1]
	v_pk_mul_f32 v[98:99], v[98:99], v[230:231] op_sel:[0,1] op_sel_hi:[1,1]
	v_pk_mul_f32 v[92:93], v[92:93], v[232:233] op_sel_hi:[1,0]
	v_pk_mul_f32 v[94:95], v[94:95], v[232:233] op_sel_hi:[1,0]
	v_pk_mul_f32 v[88:89], v[88:89], v[232:233] op_sel_hi:[1,0]
	v_pk_mul_f32 v[90:91], v[90:91], v[232:233] op_sel_hi:[1,0]
	v_pk_mul_f32 v[84:85], v[84:85], v[232:233] op_sel_hi:[1,0]
	v_pk_mul_f32 v[86:87], v[86:87], v[232:233] op_sel_hi:[1,0]
	v_pk_mul_f32 v[80:81], v[80:81], v[232:233] op_sel_hi:[1,0]
	v_pk_mul_f32 v[82:83], v[82:83], v[232:233] op_sel_hi:[1,0]
	v_pk_mul_f32 v[36:37], v[36:37], v[232:233] op_sel:[0,1] op_sel_hi:[1,1]
	v_pk_mul_f32 v[38:39], v[38:39], v[232:233] op_sel:[0,1] op_sel_hi:[1,1]
	v_pk_mul_f32 v[12:13], v[12:13], v[232:233] op_sel:[0,1] op_sel_hi:[1,1]
	v_pk_mul_f32 v[14:15], v[14:15], v[232:233] op_sel:[0,1] op_sel_hi:[1,1]
	v_pk_mul_f32 v[28:29], v[28:29], v[232:233] op_sel:[0,1] op_sel_hi:[1,1]
	v_pk_mul_f32 v[30:31], v[30:31], v[232:233] op_sel:[0,1] op_sel_hi:[1,1]
	v_pk_mul_f32 v[8:9], v[8:9], v[232:233] op_sel:[0,1] op_sel_hi:[1,1]
	v_pk_mul_f32 v[10:11], v[10:11], v[232:233] op_sel:[0,1] op_sel_hi:[1,1]
	v_pk_mul_f32 v[32:33], v[32:33], v[234:235] op_sel_hi:[1,0]
	v_pk_mul_f32 v[34:35], v[34:35], v[234:235] op_sel_hi:[1,0]
	v_pk_mul_f32 v[4:5], v[4:5], v[234:235] op_sel_hi:[1,0]
	v_pk_mul_f32 v[6:7], v[6:7], v[234:235] op_sel_hi:[1,0]
	v_pk_mul_f32 v[24:25], v[24:25], v[234:235] op_sel_hi:[1,0]
	v_pk_mul_f32 v[26:27], v[26:27], v[234:235] op_sel_hi:[1,0]
	v_pk_mul_f32 v[0:1], v[0:1], v[234:235] op_sel_hi:[1,0]
	v_pk_mul_f32 v[2:3], v[2:3], v[234:235] op_sel_hi:[1,0]
	v_pk_mul_f32 v[76:77], v[76:77], v[234:235] op_sel:[0,1] op_sel_hi:[1,1]
	v_pk_mul_f32 v[78:79], v[78:79], v[234:235] op_sel:[0,1] op_sel_hi:[1,1]
	v_pk_mul_f32 v[56:57], v[56:57], v[234:235] op_sel:[0,1] op_sel_hi:[1,1]
	v_pk_mul_f32 v[58:59], v[58:59], v[234:235] op_sel:[0,1] op_sel_hi:[1,1]
	v_pk_mul_f32 v[72:73], v[72:73], v[234:235] op_sel:[0,1] op_sel_hi:[1,1]
	v_pk_mul_f32 v[74:75], v[74:75], v[234:235] op_sel:[0,1] op_sel_hi:[1,1]
	v_pk_mul_f32 v[40:41], v[40:41], v[234:235] op_sel:[0,1] op_sel_hi:[1,1]
	v_pk_mul_f32 v[42:43], v[42:43], v[234:235] op_sel:[0,1] op_sel_hi:[1,1]
	s_waitcnt vmcnt(0)
	ds_write_b128 v195, v[224:227] offset:49152
	s_waitcnt lgkmcnt(0)
; __device__ __forceinline__ unsigned cvt_pk_bf16(float lo, float hi) { unsigned r; asm volatile("v_cvt_pk_bf16_f32 %0, %1, %2" : "=v"(r) : "v"(lo), "v"(hi)); return r; }
;     __device__ __forceinline__ void operator()(f32x4 (&acc)[2][2][4][2], const Unit& u, int wr, int wc, int fr, int fq, const LAS float* rtab) const {
;     ...
; #pragma unroll
;         for (int ai = 0; ai < 2; ++ai) {
;             const int blk = (u.pm * BM + ai * HALF + wr * 64) >> 6;
;             if (fr < 2) { bf16_t* rp = raw + ((size_t)blk * 4 + fr) * UP_N + c0;
;                 const f32x4 g0 = acc[ai][0][0][0], g1 = acc[ai][0][0][1], u0 = acc[ai][1][0][0], u1 = acc[ai][1][0][1];
;                 u32x4 w; w.x = cvt_pk_bf16(g0[0], g0[1]); w.y = cvt_pk_bf16(g0[2], g0[3]); w.z = cvt_pk_bf16(g1[0], g1[1]); w.w = cvt_pk_bf16(g1[2], g1[3]); *(u32x4*)rp = w;
;                 w.x = cvt_pk_bf16(u0[0], u0[1]); w.y = cvt_pk_bf16(u0[2], u0[3]); w.z = cvt_pk_bf16(u1[0], u1[1]); w.w = cvt_pk_bf16(u1[2], u1[3]); *(u32x4*)(rp + DFF) = w; }
;             if (fr >= 14) { bf16_t* rp = raw + ((size_t)blk * 4 + (fr - 12)) * UP_N + c0;
;                 const f32x4 g0 = acc[ai][0][3][0], g1 = acc[ai][0][3][1], u0 = acc[ai][1][3][0], u1 = acc[ai][1][3][1];
;                 u32x4 w; w.x = cvt_pk_bf16(g0[0], g0[1]); w.y = cvt_pk_bf16(g0[2], g0[3]); w.z = cvt_pk_bf16(g1[0], g1[1]); w.w = cvt_pk_bf16(g1[2], g1[3]); *(u32x4*)rp = w;
;                 w.x = cvt_pk_bf16(u0[0], u0[1]); w.y = cvt_pk_bf16(u0[2], u0[3]); w.z = cvt_pk_bf16(u1[0], u1[1]); w.w = cvt_pk_bf16(u1[2], u1[3]); *(u32x4*)(rp + DFF) = w; }
;         }
;         u32x2 ypk[2][4];
; #pragma unroll
;         for (int n = 0; n < 2; ++n) {
;             const int cn = c0 + 4 * n;
;             const f32x4 wg0 = *(const f32x4*)(cw + cn), wg1 = *(const f32x4*)(cw + UP_N + cn), wg2 = *(const f32x4*)(cw + 2 * UP_N + cn), bg = *(const f32x4*)(cb + cn);
;             const f32x4 wu0 = *(const f32x4*)(cw + DFF + cn), wu1 = *(const f32x4*)(cw + UP_N + DFF + cn), wu2 = *(const f32x4*)(cw + 2 * UP_N + DFF + cn), bu = *(const f32x4*)(cb + DFF + cn);
	ds_read_b128 v[144:147], v212 offset:49152
	ds_read_b128 v[152:155], v212 offset:49184
	ds_read_b128 v[160:163], v212 offset:49216
	ds_read_b128 v[168:171], v212 offset:49248
	ds_read_b128 v[180:183], v212 offset:49280
	ds_read_b128 v[188:191], v212 offset:49312
	ds_read_b128 v[200:203], v212 offset:49344
	ds_read_b128 v[220:223], v212 offset:49376
	ds_read_b128 v[148:151], v212 offset:49168
	ds_read_b128 v[156:159], v212 offset:49200
	ds_read_b128 v[164:167], v212 offset:49232
	ds_read_b128 v[172:175], v212 offset:49264
	ds_read_b128 v[184:187], v212 offset:49296
	ds_read_b128 v[196:199], v212 offset:49328
	ds_read_b128 v[204:207], v212 offset:49360
	ds_read_b128 v[224:227], v212 offset:49392
	v_lshlrev_b32_e32 v235, 1, v213
	s_lshl_b32 s0, s18, 8
	s_add_i32 s0, s0, s69
	v_lshl_add_u32 v234, v134, 2, s0
	v_mul_lo_u32 v234, v234, s89
	v_add_u32_e32 v234, v234, v235
	v_cmp_eq_u32_e64 s[54:55], 0, v134
	v_cmp_eq_u32_e64 s[56:57], 15, v134
	s_lshl_b32 s0, s18, 4
	s_lshr_b32 s1, s69, 4
	s_add_i32 s0, s0, s1
	s_add_i32 s1, s0, 0
	s_mul_i32 s1, s1, s88
	s_add_u32 s58, s30, s1
	s_addc_u32 s59, s31, 0
	s_mov_b64 exec, s[54:55]
	v_cvt_pk_bf16_f32 v244, v124, v125
	v_cvt_pk_bf16_f32 v245, v126, v127
	v_cvt_pk_bf16_f32 v246, v120, v121
	v_cvt_pk_bf16_f32 v247, v122, v123
	v_cvt_pk_bf16_f32 v248, v116, v117
	v_cvt_pk_bf16_f32 v249, v118, v119
	v_cvt_pk_bf16_f32 v250, v112, v113
	v_cvt_pk_bf16_f32 v251, v114, v115
	global_store_dwordx4 v235, v[244:247], s[58:59]
	s_add_u32 s58, s58, 0x2c00
	s_addc_u32 s59, s59, 0
	global_store_dwordx4 v235, v[248:251], s[58:59]
	s_add_i32 s1, s0, 1
	s_mul_i32 s1, s1, s88
	s_add_u32 s58, s30, s1
	s_addc_u32 s59, s31, 0
	s_mov_b64 exec, s[54:55]
	v_cvt_pk_bf16_f32 v236, v68, v69
	v_cvt_pk_bf16_f32 v237, v70, v71
	v_cvt_pk_bf16_f32 v238, v64, v65
	v_cvt_pk_bf16_f32 v239, v66, v67
	v_cvt_pk_bf16_f32 v240, v52, v53
	v_cvt_pk_bf16_f32 v241, v54, v55
	v_cvt_pk_bf16_f32 v242, v48, v49
	v_cvt_pk_bf16_f32 v243, v50, v51
	global_store_dwordx4 v235, v[236:239], s[58:59]
	s_add_u32 s58, s58, 0x2c00
	s_addc_u32 s59, s59, 0
	global_store_dwordx4 v235, v[240:243], s[58:59]
	s_add_i32 s1, s0, 2
	s_mul_i32 s1, s1, s88
	s_add_u32 s58, s30, s1
	s_addc_u32 s59, s31, 0
	s_mov_b64 exec, s[56:57]
	v_cvt_pk_bf16_f32 v244, v60, v61
	v_cvt_pk_bf16_f32 v245, v62, v63
	v_cvt_pk_bf16_f32 v246, v20, v21
	v_cvt_pk_bf16_f32 v247, v22, v23
	v_cvt_pk_bf16_f32 v248, v44, v45
	v_cvt_pk_bf16_f32 v249, v46, v47
	v_cvt_pk_bf16_f32 v250, v16, v17
	v_cvt_pk_bf16_f32 v251, v18, v19
	global_store_dwordx4 v235, v[244:247], s[58:59]
	s_add_u32 s58, s58, 0x2c00
	s_addc_u32 s59, s59, 0
	global_store_dwordx4 v235, v[248:251], s[58:59]
	s_add_i32 s1, s0, 3
	s_mul_i32 s1, s1, s88
	s_add_u32 s58, s30, s1
	s_addc_u32 s59, s31, 0
	s_mov_b64 exec, s[56:57]
	v_cvt_pk_bf16_f32 v236, v108, v109
	v_cvt_pk_bf16_f32 v237, v110, v111
	v_cvt_pk_bf16_f32 v238, v104, v105
	v_cvt_pk_bf16_f32 v239, v106, v107
	v_cvt_pk_bf16_f32 v240, v100, v101
	v_cvt_pk_bf16_f32 v241, v102, v103
	v_cvt_pk_bf16_f32 v242, v96, v97
	v_cvt_pk_bf16_f32 v243, v98, v99
	global_store_dwordx4 v235, v[236:239], s[58:59]
	s_add_u32 s58, s58, 0x2c00
	s_addc_u32 s59, s59, 0
	global_store_dwordx4 v235, v[240:243], s[58:59]
	s_add_i32 s1, s0, 8
	s_mul_i32 s1, s1, s88
	s_add_u32 s58, s30, s1
	s_addc_u32 s59, s31, 0
	s_mov_b64 exec, s[54:55]
	v_cvt_pk_bf16_f32 v244, v92, v93
	v_cvt_pk_bf16_f32 v245, v94, v95
	v_cvt_pk_bf16_f32 v246, v88, v89
	v_cvt_pk_bf16_f32 v247, v90, v91
	v_cvt_pk_bf16_f32 v248, v84, v85
	v_cvt_pk_bf16_f32 v249, v86, v87
	v_cvt_pk_bf16_f32 v250, v80, v81
	v_cvt_pk_bf16_f32 v251, v82, v83
	global_store_dwordx4 v235, v[244:247], s[58:59]
	s_add_u32 s58, s58, 0x2c00
	s_addc_u32 s59, s59, 0
	global_store_dwordx4 v235, v[248:251], s[58:59]
	s_add_i32 s1, s0, 9
	s_mul_i32 s1, s1, s88
	s_add_u32 s58, s30, s1
	s_addc_u32 s59, s31, 0
	s_mov_b64 exec, s[54:55]
	v_cvt_pk_bf16_f32 v236, v36, v37
	v_cvt_pk_bf16_f32 v237, v38, v39
	v_cvt_pk_bf16_f32 v238, v12, v13
	v_cvt_pk_bf16_f32 v239, v14, v15
	v_cvt_pk_bf16_f32 v240, v28, v29
	v_cvt_pk_bf16_f32 v241, v30, v31
	v_cvt_pk_bf16_f32 v242, v8, v9
	v_cvt_pk_bf16_f32 v243, v10, v11
	global_store_dwordx4 v235, v[236:239], s[58:59]
	s_add_u32 s58, s58, 0x2c00
	s_addc_u32 s59, s59, 0
	global_store_dwordx4 v235, v[240:243], s[58:59]
	s_add_i32 s1, s0, 10
	s_mul_i32 s1, s1, s88
	s_add_u32 s58, s30, s1
	s_addc_u32 s59, s31, 0
	s_mov_b64 exec, s[56:57]
	v_cvt_pk_bf16_f32 v244, v32, v33
	v_cvt_pk_bf16_f32 v245, v34, v35
	v_cvt_pk_bf16_f32 v246, v4, v5
	v_cvt_pk_bf16_f32 v247, v6, v7
	v_cvt_pk_bf16_f32 v248, v24, v25
	v_cvt_pk_bf16_f32 v249, v26, v27
	v_cvt_pk_bf16_f32 v250, v0, v1
	v_cvt_pk_bf16_f32 v251, v2, v3
	global_store_dwordx4 v235, v[244:247], s[58:59]
	s_add_u32 s58, s58, 0x2c00
	s_addc_u32 s59, s59, 0
	global_store_dwordx4 v235, v[248:251], s[58:59]
	s_add_i32 s1, s0, 11
	s_mul_i32 s1, s1, s88
	s_add_u32 s58, s30, s1
	s_addc_u32 s59, s31, 0
	s_mov_b64 exec, s[56:57]
	v_cvt_pk_bf16_f32 v236, v76, v77
	v_cvt_pk_bf16_f32 v237, v78, v79
	v_cvt_pk_bf16_f32 v238, v56, v57
	v_cvt_pk_bf16_f32 v239, v58, v59
	v_cvt_pk_bf16_f32 v240, v72, v73
	v_cvt_pk_bf16_f32 v241, v74, v75
	v_cvt_pk_bf16_f32 v242, v40, v41
	v_cvt_pk_bf16_f32 v243, v42, v43
	global_store_dwordx4 v235, v[236:239], s[58:59]
	s_add_u32 s58, s58, 0x2c00
	s_addc_u32 s59, s59, 0
	global_store_dwordx4 v235, v[240:243], s[58:59]
	s_mov_b64 exec, -1
	s_waitcnt lgkmcnt(12)
; __device__ __forceinline__ unsigned cvt_pk_bf16(float lo, float hi) { unsigned r; asm volatile("v_cvt_pk_bf16_f32 %0, %1, %2" : "=v"(r) : "v"(lo), "v"(hi)); return r; }
; template <int CTRL> __device__ __forceinline__ float dppz(float v) { return __int_as_float(__builtin_amdgcn_update_dpp(0, __float_as_int(v), CTRL, 0xf, 0xf, true)); }
;     __device__ __forceinline__ void operator()(f32x4 (&acc)[2][2][4][2], const Unit& u, int wr, int wc, int fr, int fq, const LAS float* rtab) const {
;     ...
;                 for (int m = 0; m < 4; ++m) {
;                     float y[4];
; #pragma unroll
;                     for (int jj = 0; jj < 4; ++jj) {
;                         const float gc = acc[ai][0][m][n][jj], uc = acc[ai][1][m][n][jj];
;                         const float gb = m > 0 ? acc[ai][0][m - 1][n][jj] : 0.f, ga = m < 3 ? acc[ai][0][m + 1][n][jj] : 0.f;
;                         const float ub = m > 0 ? acc[ai][1][m - 1][n][jj] : 0.f, ua = m < 3 ? acc[ai][1][m + 1][n][jj] : 0.f;
;                         const float gp = dppz<0x111>(gc) + dppz<0x10F>(gb), gn = dppz<0x101>(gc) + dppz<0x11F>(ga);
;                         const float up = dppz<0x111>(uc) + dppz<0x10F>(ub), un = dppz<0x101>(uc) + dppz<0x11F>(ua);
;                         const float hg = wg0[jj] * gp + wg1[jj] * gc + wg2[jj] * gn + bg[jj];
;                         const float hu = wu0[jj] * up + wu1[jj] * uc + wu2[jj] * un + bu[jj];
;                         const float sg = __builtin_amdgcn_rcpf(1.f + __builtin_amdgcn_exp2f(-1.4426950408889634f * hg));
;                         y[jj] = hg * sg * hu; }
;                     u32x2 pk; pk.x = cvt_pk_bf16(y[0], y[1]); pk.y = cvt_pk_bf16(y[2], y[3]);
	s_mov_b32 s54, 0xbfb8aa3b
	s_mov_b32 s56, 1.0
	v_pk_fma_f32 v[142:143], v[152:153], v[124:125], v[168:169]
	v_pk_fma_f32 v[178:179], v[152:153], v[68:69], v[168:169]
	v_pk_fma_f32 v[210:211], v[152:153], v[60:61], v[168:169]
	v_pk_fma_f32 v[212:213], v[152:153], v[108:109], v[168:169]
	v_pk_fma_f32 v[142:143], v[160:161], v[68:69], v[142:143]
	v_pk_fma_f32 v[178:179], v[144:145], v[124:125], v[178:179]
	v_pk_fma_f32 v[210:211], v[144:145], v[68:69], v[210:211]
	v_pk_fma_f32 v[212:213], v[144:145], v[60:61], v[212:213]
	v_pk_fma_f32 v[178:179], v[160:161], v[60:61], v[178:179]
	v_pk_fma_f32 v[210:211], v[160:161], v[108:109], v[210:211]
	v_fmac_f32_dpp v142, v108, v144 row_shr:1 row_mask:0xf bank_mask:0xf bound_ctrl:1
	v_fmac_f32_dpp v212, v124, v160 row_shl:1 row_mask:0xf bank_mask:0xf bound_ctrl:1
	v_fmac_f32_dpp v143, v109, v145 row_shr:1 row_mask:0xf bank_mask:0xf bound_ctrl:1
	v_fmac_f32_dpp v213, v125, v161 row_shl:1 row_mask:0xf bank_mask:0xf bound_ctrl:1
	v_pk_mul_f32 v[218:219], v[142:143], s[54:55] op_sel_hi:[1,0]
	v_pk_mul_f32 v[252:253], v[178:179], s[54:55] op_sel_hi:[1,0]
	v_pk_mul_f32 v[228:229], v[210:211], s[54:55] op_sel_hi:[1,0]
	v_pk_mul_f32 v[230:231], v[212:213], s[54:55] op_sel_hi:[1,0]
	v_exp_f32_e32 v218, v218
	v_exp_f32_e32 v219, v219
	v_exp_f32_e32 v252, v252
	v_exp_f32_e32 v253, v253
	v_exp_f32_e32 v228, v228
	v_exp_f32_e32 v229, v229
	v_exp_f32_e32 v230, v230
	v_exp_f32_e32 v231, v231
	v_pk_add_f32 v[218:219], v[218:219], s[56:57] op_sel_hi:[1,0]
	v_pk_add_f32 v[252:253], v[252:253], s[56:57] op_sel_hi:[1,0]
	v_pk_add_f32 v[228:229], v[228:229], s[56:57] op_sel_hi:[1,0]
	v_pk_add_f32 v[230:231], v[230:231], s[56:57] op_sel_hi:[1,0]
	v_rcp_f32_e32 v218, v218
	v_rcp_f32_e32 v219, v219
	v_rcp_f32_e32 v252, v252
	v_rcp_f32_e32 v253, v253
	v_rcp_f32_e32 v228, v228
	v_rcp_f32_e32 v229, v229
	v_rcp_f32_e32 v230, v230
	v_rcp_f32_e32 v231, v231
	v_pk_mul_f32 v[142:143], v[142:143], v[218:219]
	v_pk_mul_f32 v[178:179], v[178:179], v[252:253]
	v_pk_mul_f32 v[210:211], v[210:211], v[228:229]
	v_pk_mul_f32 v[212:213], v[212:213], v[230:231]
	s_waitcnt lgkmcnt(8)
	v_pk_fma_f32 v[218:219], v[188:189], v[116:117], v[220:221]
	v_pk_fma_f32 v[252:253], v[188:189], v[52:53], v[220:221]
	v_pk_fma_f32 v[228:229], v[188:189], v[44:45], v[220:221]
	v_pk_fma_f32 v[230:231], v[188:189], v[100:101], v[220:221]
	v_pk_fma_f32 v[218:219], v[200:201], v[52:53], v[218:219]
	v_pk_fma_f32 v[252:253], v[180:181], v[116:117], v[252:253]
	v_pk_fma_f32 v[228:229], v[180:181], v[52:53], v[228:229]
	v_pk_fma_f32 v[230:231], v[180:181], v[44:45], v[230:231]
	v_pk_fma_f32 v[252:253], v[200:201], v[44:45], v[252:253]
	v_pk_fma_f32 v[228:229], v[200:201], v[100:101], v[228:229]
	v_fmac_f32_dpp v218, v100, v180 row_shr:1 row_mask:0xf bank_mask:0xf bound_ctrl:1
	v_fmac_f32_dpp v230, v116, v200 row_shl:1 row_mask:0xf bank_mask:0xf bound_ctrl:1
	v_fmac_f32_dpp v219, v101, v181 row_shr:1 row_mask:0xf bank_mask:0xf bound_ctrl:1
	v_fmac_f32_dpp v231, v117, v201 row_shl:1 row_mask:0xf bank_mask:0xf bound_ctrl:1
	v_pk_mul_f32 v[142:143], v[142:143], v[218:219]
	v_pk_mul_f32 v[178:179], v[178:179], v[252:253]
	v_pk_mul_f32 v[210:211], v[210:211], v[228:229]
	v_pk_mul_f32 v[212:213], v[212:213], v[230:231]
	v_cvt_pk_bf16_f32 v236, v142, v143
	v_cvt_pk_bf16_f32 v240, v178, v179
	v_cvt_pk_bf16_f32 v244, v210, v211
	v_cvt_pk_bf16_f32 v248, v212, v213
	v_pk_fma_f32 v[142:143], v[154:155], v[126:127], v[170:171]
	v_pk_fma_f32 v[178:179], v[154:155], v[70:71], v[170:171]
	v_pk_fma_f32 v[210:211], v[154:155], v[62:63], v[170:171]
	v_pk_fma_f32 v[212:213], v[154:155], v[110:111], v[170:171]
	v_pk_fma_f32 v[142:143], v[162:163], v[70:71], v[142:143]
	v_pk_fma_f32 v[178:179], v[146:147], v[126:127], v[178:179]
	v_pk_fma_f32 v[210:211], v[146:147], v[70:71], v[210:211]
	v_pk_fma_f32 v[212:213], v[146:147], v[62:63], v[212:213]
	v_pk_fma_f32 v[178:179], v[162:163], v[62:63], v[178:179]
	v_pk_fma_f32 v[210:211], v[162:163], v[110:111], v[210:211]
	v_fmac_f32_dpp v142, v110, v146 row_shr:1 row_mask:0xf bank_mask:0xf bound_ctrl:1
	v_fmac_f32_dpp v212, v126, v162 row_shl:1 row_mask:0xf bank_mask:0xf bound_ctrl:1
	v_fmac_f32_dpp v143, v111, v147 row_shr:1 row_mask:0xf bank_mask:0xf bound_ctrl:1
	v_fmac_f32_dpp v213, v127, v163 row_shl:1 row_mask:0xf bank_mask:0xf bound_ctrl:1
	v_pk_mul_f32 v[218:219], v[142:143], s[54:55] op_sel_hi:[1,0]
	v_pk_mul_f32 v[252:253], v[178:179], s[54:55] op_sel_hi:[1,0]
	v_pk_mul_f32 v[228:229], v[210:211], s[54:55] op_sel_hi:[1,0]
	v_pk_mul_f32 v[230:231], v[212:213], s[54:55] op_sel_hi:[1,0]
	v_exp_f32_e32 v218, v218
	v_exp_f32_e32 v219, v219
	v_exp_f32_e32 v252, v252
	v_exp_f32_e32 v253, v253
	v_exp_f32_e32 v228, v228
	v_exp_f32_e32 v229, v229
	v_exp_f32_e32 v230, v230
	v_exp_f32_e32 v231, v231
	v_pk_add_f32 v[218:219], v[218:219], s[56:57] op_sel_hi:[1,0]
	v_pk_add_f32 v[252:253], v[252:253], s[56:57] op_sel_hi:[1,0]
	v_pk_add_f32 v[228:229], v[228:229], s[56:57] op_sel_hi:[1,0]
	v_pk_add_f32 v[230:231], v[230:231], s[56:57] op_sel_hi:[1,0]
	v_rcp_f32_e32 v218, v218
	v_rcp_f32_e32 v219, v219
	v_rcp_f32_e32 v252, v252
	v_rcp_f32_e32 v253, v253
	v_rcp_f32_e32 v228, v228
	v_rcp_f32_e32 v229, v229
	v_rcp_f32_e32 v230, v230
	v_rcp_f32_e32 v231, v231
	v_pk_mul_f32 v[142:143], v[142:143], v[218:219]
	v_pk_mul_f32 v[178:179], v[178:179], v[252:253]
	v_pk_mul_f32 v[210:211], v[210:211], v[228:229]
	v_pk_mul_f32 v[212:213], v[212:213], v[230:231]
	v_pk_fma_f32 v[218:219], v[190:191], v[118:119], v[222:223]
	v_pk_fma_f32 v[252:253], v[190:191], v[54:55], v[222:223]
	v_pk_fma_f32 v[228:229], v[190:191], v[46:47], v[222:223]
	v_pk_fma_f32 v[230:231], v[190:191], v[102:103], v[222:223]
	v_pk_fma_f32 v[218:219], v[202:203], v[54:55], v[218:219]
	v_pk_fma_f32 v[252:253], v[182:183], v[118:119], v[252:253]
	v_pk_fma_f32 v[228:229], v[182:183], v[54:55], v[228:229]
	v_pk_fma_f32 v[230:231], v[182:183], v[46:47], v[230:231]
	v_pk_fma_f32 v[252:253], v[202:203], v[46:47], v[252:253]
	v_pk_fma_f32 v[228:229], v[202:203], v[102:103], v[228:229]
	v_fmac_f32_dpp v218, v102, v182 row_shr:1 row_mask:0xf bank_mask:0xf bound_ctrl:1
	v_fmac_f32_dpp v230, v118, v202 row_shl:1 row_mask:0xf bank_mask:0xf bound_ctrl:1
	v_fmac_f32_dpp v219, v103, v183 row_shr:1 row_mask:0xf bank_mask:0xf bound_ctrl:1
	v_fmac_f32_dpp v231, v119, v203 row_shl:1 row_mask:0xf bank_mask:0xf bound_ctrl:1
	v_pk_mul_f32 v[142:143], v[142:143], v[218:219]
	v_pk_mul_f32 v[178:179], v[178:179], v[252:253]
	v_pk_mul_f32 v[210:211], v[210:211], v[228:229]
	v_pk_mul_f32 v[212:213], v[212:213], v[230:231]
	v_cvt_pk_bf16_f32 v237, v142, v143
	v_cvt_pk_bf16_f32 v241, v178, v179
	v_cvt_pk_bf16_f32 v245, v210, v211
	v_cvt_pk_bf16_f32 v249, v212, v213
	s_waitcnt lgkmcnt(4)
; __device__ __forceinline__ unsigned cvt_pk_bf16(float lo, float hi) { unsigned r; asm volatile("v_cvt_pk_bf16_f32 %0, %1, %2" : "=v"(r) : "v"(lo), "v"(hi)); return r; }
; template <int CTRL> __device__ __forceinline__ float dppz(float v) { return __int_as_float(__builtin_amdgcn_update_dpp(0, __float_as_int(v), CTRL, 0xf, 0xf, true)); }
;     __device__ __forceinline__ void operator()(f32x4 (&acc)[2][2][4][2], const Unit& u, int wr, int wc, int fr, int fq, const LAS float* rtab) const {
;     ...
;                 for (int m = 0; m < 4; ++m) {
;                     float y[4];
; #pragma unroll
;                     for (int jj = 0; jj < 4; ++jj) {
;                         const float gc = acc[ai][0][m][n][jj], uc = acc[ai][1][m][n][jj];
;                         const float gb = m > 0 ? acc[ai][0][m - 1][n][jj] : 0.f, ga = m < 3 ? acc[ai][0][m + 1][n][jj] : 0.f;
;                         const float ub = m > 0 ? acc[ai][1][m - 1][n][jj] : 0.f, ua = m < 3 ? acc[ai][1][m + 1][n][jj] : 0.f;
;                         const float gp = dppz<0x111>(gc) + dppz<0x10F>(gb), gn = dppz<0x101>(gc) + dppz<0x11F>(ga);
;                         const float up = dppz<0x111>(uc) + dppz<0x10F>(ub), un = dppz<0x101>(uc) + dppz<0x11F>(ua);
;                         const float hg = wg0[jj] * gp + wg1[jj] * gc + wg2[jj] * gn + bg[jj];
;                         const float hu = wu0[jj] * up + wu1[jj] * uc + wu2[jj] * un + bu[jj];
;                         const float sg = __builtin_amdgcn_rcpf(1.f + __builtin_amdgcn_exp2f(-1.4426950408889634f * hg));
;                         y[jj] = hg * sg * hu; }
;                     u32x2 pk; pk.x = cvt_pk_bf16(y[0], y[1]); pk.y = cvt_pk_bf16(y[2], y[3]);
	v_pk_fma_f32 v[142:143], v[156:157], v[120:121], v[172:173]
	v_pk_fma_f32 v[178:179], v[156:157], v[64:65], v[172:173]
	v_pk_fma_f32 v[210:211], v[156:157], v[20:21], v[172:173]
	v_pk_fma_f32 v[212:213], v[156:157], v[104:105], v[172:173]
	v_pk_fma_f32 v[142:143], v[164:165], v[64:65], v[142:143]
	v_pk_fma_f32 v[178:179], v[148:149], v[120:121], v[178:179]
	v_pk_fma_f32 v[210:211], v[148:149], v[64:65], v[210:211]
	v_pk_fma_f32 v[212:213], v[148:149], v[20:21], v[212:213]
	v_pk_fma_f32 v[178:179], v[164:165], v[20:21], v[178:179]
	v_pk_fma_f32 v[210:211], v[164:165], v[104:105], v[210:211]
	v_fmac_f32_dpp v142, v104, v148 row_shr:1 row_mask:0xf bank_mask:0xf bound_ctrl:1
	v_fmac_f32_dpp v212, v120, v164 row_shl:1 row_mask:0xf bank_mask:0xf bound_ctrl:1
	v_fmac_f32_dpp v143, v105, v149 row_shr:1 row_mask:0xf bank_mask:0xf bound_ctrl:1
	v_fmac_f32_dpp v213, v121, v165 row_shl:1 row_mask:0xf bank_mask:0xf bound_ctrl:1
	v_pk_mul_f32 v[218:219], v[142:143], s[54:55] op_sel_hi:[1,0]
	v_pk_mul_f32 v[252:253], v[178:179], s[54:55] op_sel_hi:[1,0]
	v_pk_mul_f32 v[228:229], v[210:211], s[54:55] op_sel_hi:[1,0]
	v_pk_mul_f32 v[230:231], v[212:213], s[54:55] op_sel_hi:[1,0]
	v_exp_f32_e32 v218, v218
	v_exp_f32_e32 v219, v219
	v_exp_f32_e32 v252, v252
	v_exp_f32_e32 v253, v253
	v_exp_f32_e32 v228, v228
	v_exp_f32_e32 v229, v229
	v_exp_f32_e32 v230, v230
	v_exp_f32_e32 v231, v231
	v_pk_add_f32 v[218:219], v[218:219], s[56:57] op_sel_hi:[1,0]
	v_pk_add_f32 v[252:253], v[252:253], s[56:57] op_sel_hi:[1,0]
	v_pk_add_f32 v[228:229], v[228:229], s[56:57] op_sel_hi:[1,0]
	v_pk_add_f32 v[230:231], v[230:231], s[56:57] op_sel_hi:[1,0]
	v_rcp_f32_e32 v218, v218
	v_rcp_f32_e32 v219, v219
	v_rcp_f32_e32 v252, v252
	v_rcp_f32_e32 v253, v253
	v_rcp_f32_e32 v228, v228
	v_rcp_f32_e32 v229, v229
	v_rcp_f32_e32 v230, v230
	v_rcp_f32_e32 v231, v231
	v_pk_mul_f32 v[142:143], v[142:143], v[218:219]
	v_pk_mul_f32 v[178:179], v[178:179], v[252:253]
	v_pk_mul_f32 v[210:211], v[210:211], v[228:229]
	v_pk_mul_f32 v[212:213], v[212:213], v[230:231]
	s_waitcnt lgkmcnt(0)
	v_pk_fma_f32 v[218:219], v[196:197], v[112:113], v[224:225]
	v_pk_fma_f32 v[252:253], v[196:197], v[48:49], v[224:225]
	v_pk_fma_f32 v[228:229], v[196:197], v[16:17], v[224:225]
	v_pk_fma_f32 v[230:231], v[196:197], v[96:97], v[224:225]
	v_pk_fma_f32 v[218:219], v[204:205], v[48:49], v[218:219]
	v_pk_fma_f32 v[252:253], v[184:185], v[112:113], v[252:253]
	v_pk_fma_f32 v[228:229], v[184:185], v[48:49], v[228:229]
	v_pk_fma_f32 v[230:231], v[184:185], v[16:17], v[230:231]
	v_pk_fma_f32 v[252:253], v[204:205], v[16:17], v[252:253]
	v_pk_fma_f32 v[228:229], v[204:205], v[96:97], v[228:229]
	v_fmac_f32_dpp v218, v96, v184 row_shr:1 row_mask:0xf bank_mask:0xf bound_ctrl:1
	v_fmac_f32_dpp v230, v112, v204 row_shl:1 row_mask:0xf bank_mask:0xf bound_ctrl:1
	v_fmac_f32_dpp v219, v97, v185 row_shr:1 row_mask:0xf bank_mask:0xf bound_ctrl:1
	v_fmac_f32_dpp v231, v113, v205 row_shl:1 row_mask:0xf bank_mask:0xf bound_ctrl:1
	v_pk_mul_f32 v[142:143], v[142:143], v[218:219]
	v_pk_mul_f32 v[178:179], v[178:179], v[252:253]
	v_pk_mul_f32 v[210:211], v[210:211], v[228:229]
	v_pk_mul_f32 v[212:213], v[212:213], v[230:231]
	v_cvt_pk_bf16_f32 v238, v142, v143
	v_cvt_pk_bf16_f32 v242, v178, v179
	v_cvt_pk_bf16_f32 v246, v210, v211
	v_cvt_pk_bf16_f32 v250, v212, v213
	v_pk_fma_f32 v[142:143], v[158:159], v[122:123], v[174:175]
	v_pk_fma_f32 v[178:179], v[158:159], v[66:67], v[174:175]
	v_pk_fma_f32 v[210:211], v[158:159], v[22:23], v[174:175]
	v_pk_fma_f32 v[212:213], v[158:159], v[106:107], v[174:175]
	v_pk_fma_f32 v[142:143], v[166:167], v[66:67], v[142:143]
	v_pk_fma_f32 v[178:179], v[150:151], v[122:123], v[178:179]
	v_pk_fma_f32 v[210:211], v[150:151], v[66:67], v[210:211]
	v_pk_fma_f32 v[212:213], v[150:151], v[22:23], v[212:213]
	v_pk_fma_f32 v[178:179], v[166:167], v[22:23], v[178:179]
	v_pk_fma_f32 v[210:211], v[166:167], v[106:107], v[210:211]
	v_fmac_f32_dpp v142, v106, v150 row_shr:1 row_mask:0xf bank_mask:0xf bound_ctrl:1
	v_fmac_f32_dpp v212, v122, v166 row_shl:1 row_mask:0xf bank_mask:0xf bound_ctrl:1
	v_fmac_f32_dpp v143, v107, v151 row_shr:1 row_mask:0xf bank_mask:0xf bound_ctrl:1
	v_fmac_f32_dpp v213, v123, v167 row_shl:1 row_mask:0xf bank_mask:0xf bound_ctrl:1
	v_pk_mul_f32 v[218:219], v[142:143], s[54:55] op_sel_hi:[1,0]
	v_pk_mul_f32 v[252:253], v[178:179], s[54:55] op_sel_hi:[1,0]
	v_pk_mul_f32 v[228:229], v[210:211], s[54:55] op_sel_hi:[1,0]
	v_pk_mul_f32 v[230:231], v[212:213], s[54:55] op_sel_hi:[1,0]
	v_exp_f32_e32 v218, v218
	v_exp_f32_e32 v219, v219
	v_exp_f32_e32 v252, v252
	v_exp_f32_e32 v253, v253
	v_exp_f32_e32 v228, v228
	v_exp_f32_e32 v229, v229
	v_exp_f32_e32 v230, v230
	v_exp_f32_e32 v231, v231
	v_pk_add_f32 v[218:219], v[218:219], s[56:57] op_sel_hi:[1,0]
	v_pk_add_f32 v[252:253], v[252:253], s[56:57] op_sel_hi:[1,0]
	v_pk_add_f32 v[228:229], v[228:229], s[56:57] op_sel_hi:[1,0]
	v_pk_add_f32 v[230:231], v[230:231], s[56:57] op_sel_hi:[1,0]
	v_rcp_f32_e32 v218, v218
	v_rcp_f32_e32 v219, v219
	v_rcp_f32_e32 v252, v252
	v_rcp_f32_e32 v253, v253
	v_rcp_f32_e32 v228, v228
	v_rcp_f32_e32 v229, v229
	v_rcp_f32_e32 v230, v230
	v_rcp_f32_e32 v231, v231
	v_pk_mul_f32 v[142:143], v[142:143], v[218:219]
	v_pk_mul_f32 v[178:179], v[178:179], v[252:253]
	v_pk_mul_f32 v[210:211], v[210:211], v[228:229]
	v_pk_mul_f32 v[212:213], v[212:213], v[230:231]
	v_pk_fma_f32 v[218:219], v[198:199], v[114:115], v[226:227]
	v_pk_fma_f32 v[252:253], v[198:199], v[50:51], v[226:227]
	v_pk_fma_f32 v[228:229], v[198:199], v[18:19], v[226:227]
	v_pk_fma_f32 v[230:231], v[198:199], v[98:99], v[226:227]
; __device__ __forceinline__ unsigned cvt_pk_bf16(float lo, float hi) { unsigned r; asm volatile("v_cvt_pk_bf16_f32 %0, %1, %2" : "=v"(r) : "v"(lo), "v"(hi)); return r; }
; template <int CTRL> __device__ __forceinline__ float dppz(float v) { return __int_as_float(__builtin_amdgcn_update_dpp(0, __float_as_int(v), CTRL, 0xf, 0xf, true)); }
;     __device__ __forceinline__ void operator()(f32x4 (&acc)[2][2][4][2], const Unit& u, int wr, int wc, int fr, int fq, const LAS float* rtab) const {
;     ...
;                     for (int jj = 0; jj < 4; ++jj) {
;                         const float gc = acc[ai][0][m][n][jj], uc = acc[ai][1][m][n][jj];
;                         const float gb = m > 0 ? acc[ai][0][m - 1][n][jj] : 0.f, ga = m < 3 ? acc[ai][0][m + 1][n][jj] : 0.f;
;                         const float ub = m > 0 ? acc[ai][1][m - 1][n][jj] : 0.f, ua = m < 3 ? acc[ai][1][m + 1][n][jj] : 0.f;
;                         const float gp = dppz<0x111>(gc) + dppz<0x10F>(gb), gn = dppz<0x101>(gc) + dppz<0x11F>(ga);
;                         const float up = dppz<0x111>(uc) + dppz<0x10F>(ub), un = dppz<0x101>(uc) + dppz<0x11F>(ua);
;                         const float hg = wg0[jj] * gp + wg1[jj] * gc + wg2[jj] * gn + bg[jj];
;                         const float hu = wu0[jj] * up + wu1[jj] * uc + wu2[jj] * un + bu[jj];
;                         const float sg = __builtin_amdgcn_rcpf(1.f + __builtin_amdgcn_exp2f(-1.4426950408889634f * hg));
;                         y[jj] = hg * sg * hu; }
;                     u32x2 pk; pk.x = cvt_pk_bf16(y[0], y[1]); pk.y = cvt_pk_bf16(y[2], y[3]);
;                     if (n == 0) ypk[ai][m] = pk;
;                     else {
;                         const bool deferred = (m == 0 && fr == 0) || (m == 3 && fr == 15);
;                         if (!deferred) { u32x4 w; w.x = ypk[ai][m].x; w.y = ypk[ai][m].y; w.z = pk.x; w.w = pk.y; *(u32x4*)(act + (size_t)(r64 + m * 16 + fr) * DFF + c0) = w; } }
	v_pk_fma_f32 v[218:219], v[206:207], v[50:51], v[218:219]
	v_pk_fma_f32 v[252:253], v[186:187], v[114:115], v[252:253]
	v_pk_fma_f32 v[228:229], v[186:187], v[50:51], v[228:229]
	v_pk_fma_f32 v[230:231], v[186:187], v[18:19], v[230:231]
	v_pk_fma_f32 v[252:253], v[206:207], v[18:19], v[252:253]
	v_pk_fma_f32 v[228:229], v[206:207], v[98:99], v[228:229]
	v_fmac_f32_dpp v218, v98, v186 row_shr:1 row_mask:0xf bank_mask:0xf bound_ctrl:1
	v_fmac_f32_dpp v230, v114, v206 row_shl:1 row_mask:0xf bank_mask:0xf bound_ctrl:1
	v_fmac_f32_dpp v219, v99, v187 row_shr:1 row_mask:0xf bank_mask:0xf bound_ctrl:1
	v_fmac_f32_dpp v231, v115, v207 row_shl:1 row_mask:0xf bank_mask:0xf bound_ctrl:1
	v_pk_mul_f32 v[142:143], v[142:143], v[218:219]
	v_pk_mul_f32 v[178:179], v[178:179], v[252:253]
	v_pk_mul_f32 v[210:211], v[210:211], v[228:229]
	v_pk_mul_f32 v[212:213], v[212:213], v[230:231]
	v_cvt_pk_bf16_f32 v239, v142, v143
	v_cvt_pk_bf16_f32 v243, v178, v179
	v_cvt_pk_bf16_f32 v247, v210, v211
	v_cvt_pk_bf16_f32 v251, v212, v213
	s_mov_b64 s[58:59], s[28:29]
	s_mov_b64 exec, s[12:13]
	global_store_dwordx4 v234, v[236:239], s[58:59]
	s_mov_b64 exec, -1
	s_add_u32 s58, s28, 0x2c00
	s_addc_u32 s59, s29, 0
	global_store_dwordx4 v234, v[240:243], s[58:59]
	s_add_u32 s58, s28, 0x5800
	s_addc_u32 s59, s29, 0
	global_store_dwordx4 v234, v[244:247], s[58:59]
	s_add_u32 s58, s28, 0x8400
	s_addc_u32 s59, s29, 0
	s_mov_b64 exec, s[10:11]
	global_store_dwordx4 v234, v[248:251], s[58:59]
	s_mov_b64 exec, -1
	v_pk_fma_f32 v[142:143], v[152:153], v[92:93], v[168:169]
	v_pk_fma_f32 v[178:179], v[152:153], v[36:37], v[168:169]
	v_pk_fma_f32 v[210:211], v[152:153], v[32:33], v[168:169]
	v_pk_fma_f32 v[212:213], v[152:153], v[76:77], v[168:169]
	v_pk_fma_f32 v[142:143], v[160:161], v[36:37], v[142:143]
	v_pk_fma_f32 v[178:179], v[144:145], v[92:93], v[178:179]
	v_pk_fma_f32 v[210:211], v[144:145], v[36:37], v[210:211]
	v_pk_fma_f32 v[212:213], v[144:145], v[32:33], v[212:213]
	v_pk_fma_f32 v[178:179], v[160:161], v[32:33], v[178:179]
	v_pk_fma_f32 v[210:211], v[160:161], v[76:77], v[210:211]
	v_fmac_f32_dpp v142, v76, v144 row_shr:1 row_mask:0xf bank_mask:0xf bound_ctrl:1
	v_fmac_f32_dpp v212, v92, v160 row_shl:1 row_mask:0xf bank_mask:0xf bound_ctrl:1
	v_fmac_f32_dpp v143, v77, v145 row_shr:1 row_mask:0xf bank_mask:0xf bound_ctrl:1
	v_fmac_f32_dpp v213, v93, v161 row_shl:1 row_mask:0xf bank_mask:0xf bound_ctrl:1
	v_pk_mul_f32 v[218:219], v[142:143], s[54:55] op_sel_hi:[1,0]
	v_pk_mul_f32 v[252:253], v[178:179], s[54:55] op_sel_hi:[1,0]
	v_pk_mul_f32 v[228:229], v[210:211], s[54:55] op_sel_hi:[1,0]
	v_pk_mul_f32 v[230:231], v[212:213], s[54:55] op_sel_hi:[1,0]
	v_exp_f32_e32 v218, v218
	v_exp_f32_e32 v219, v219
	v_exp_f32_e32 v252, v252
	v_exp_f32_e32 v253, v253
	v_exp_f32_e32 v228, v228
	v_exp_f32_e32 v229, v229
	v_exp_f32_e32 v230, v230
	v_exp_f32_e32 v231, v231
	v_pk_add_f32 v[218:219], v[218:219], s[56:57] op_sel_hi:[1,0]
	v_pk_add_f32 v[252:253], v[252:253], s[56:57] op_sel_hi:[1,0]
	v_pk_add_f32 v[228:229], v[228:229], s[56:57] op_sel_hi:[1,0]
	v_pk_add_f32 v[230:231], v[230:231], s[56:57] op_sel_hi:[1,0]
	v_rcp_f32_e32 v218, v218
	v_rcp_f32_e32 v219, v219
	v_rcp_f32_e32 v252, v252
	v_rcp_f32_e32 v253, v253
	v_rcp_f32_e32 v228, v228
	v_rcp_f32_e32 v229, v229
	v_rcp_f32_e32 v230, v230
	v_rcp_f32_e32 v231, v231
	v_pk_mul_f32 v[142:143], v[142:143], v[218:219]
	v_pk_mul_f32 v[178:179], v[178:179], v[252:253]
	v_pk_mul_f32 v[210:211], v[210:211], v[228:229]
	v_pk_mul_f32 v[212:213], v[212:213], v[230:231]
	v_pk_fma_f32 v[218:219], v[188:189], v[84:85], v[220:221]
	v_pk_fma_f32 v[252:253], v[188:189], v[28:29], v[220:221]
	v_pk_fma_f32 v[228:229], v[188:189], v[24:25], v[220:221]
	v_pk_fma_f32 v[230:231], v[188:189], v[72:73], v[220:221]
	v_pk_fma_f32 v[218:219], v[200:201], v[28:29], v[218:219]
	v_pk_fma_f32 v[252:253], v[180:181], v[84:85], v[252:253]
	v_pk_fma_f32 v[228:229], v[180:181], v[28:29], v[228:229]
	v_pk_fma_f32 v[230:231], v[180:181], v[24:25], v[230:231]
	v_pk_fma_f32 v[252:253], v[200:201], v[24:25], v[252:253]
	v_pk_fma_f32 v[228:229], v[200:201], v[72:73], v[228:229]
	v_fmac_f32_dpp v218, v72, v180 row_shr:1 row_mask:0xf bank_mask:0xf bound_ctrl:1
	v_fmac_f32_dpp v230, v84, v200 row_shl:1 row_mask:0xf bank_mask:0xf bound_ctrl:1
	v_fmac_f32_dpp v219, v73, v181 row_shr:1 row_mask:0xf bank_mask:0xf bound_ctrl:1
	v_fmac_f32_dpp v231, v85, v201 row_shl:1 row_mask:0xf bank_mask:0xf bound_ctrl:1
	v_pk_mul_f32 v[142:143], v[142:143], v[218:219]
	v_pk_mul_f32 v[178:179], v[178:179], v[252:253]
	v_pk_mul_f32 v[210:211], v[210:211], v[228:229]
	v_pk_mul_f32 v[212:213], v[212:213], v[230:231]
	v_cvt_pk_bf16_f32 v236, v142, v143
	v_cvt_pk_bf16_f32 v240, v178, v179
	v_cvt_pk_bf16_f32 v244, v210, v211
	v_cvt_pk_bf16_f32 v248, v212, v213
	v_pk_fma_f32 v[142:143], v[154:155], v[94:95], v[170:171]
	v_pk_fma_f32 v[178:179], v[154:155], v[38:39], v[170:171]
	v_pk_fma_f32 v[210:211], v[154:155], v[34:35], v[170:171]
	v_pk_fma_f32 v[212:213], v[154:155], v[78:79], v[170:171]
	v_pk_fma_f32 v[142:143], v[162:163], v[38:39], v[142:143]
	v_pk_fma_f32 v[178:179], v[146:147], v[94:95], v[178:179]
	v_pk_fma_f32 v[210:211], v[146:147], v[38:39], v[210:211]
	v_pk_fma_f32 v[212:213], v[146:147], v[34:35], v[212:213]
	v_pk_fma_f32 v[178:179], v[162:163], v[34:35], v[178:179]
	v_pk_fma_f32 v[210:211], v[162:163], v[78:79], v[210:211]
	v_fmac_f32_dpp v142, v78, v146 row_shr:1 row_mask:0xf bank_mask:0xf bound_ctrl:1
	v_fmac_f32_dpp v212, v94, v162 row_shl:1 row_mask:0xf bank_mask:0xf bound_ctrl:1
	v_fmac_f32_dpp v143, v79, v147 row_shr:1 row_mask:0xf bank_mask:0xf bound_ctrl:1
; __device__ __forceinline__ unsigned cvt_pk_bf16(float lo, float hi) { unsigned r; asm volatile("v_cvt_pk_bf16_f32 %0, %1, %2" : "=v"(r) : "v"(lo), "v"(hi)); return r; }
; template <int CTRL> __device__ __forceinline__ float dppz(float v) { return __int_as_float(__builtin_amdgcn_update_dpp(0, __float_as_int(v), CTRL, 0xf, 0xf, true)); }
;     __device__ __forceinline__ void operator()(f32x4 (&acc)[2][2][4][2], const Unit& u, int wr, int wc, int fr, int fq, const LAS float* rtab) const {
;     ...
;                     for (int jj = 0; jj < 4; ++jj) {
;                         const float gc = acc[ai][0][m][n][jj], uc = acc[ai][1][m][n][jj];
;                         const float gb = m > 0 ? acc[ai][0][m - 1][n][jj] : 0.f, ga = m < 3 ? acc[ai][0][m + 1][n][jj] : 0.f;
;                         const float ub = m > 0 ? acc[ai][1][m - 1][n][jj] : 0.f, ua = m < 3 ? acc[ai][1][m + 1][n][jj] : 0.f;
;                         const float gp = dppz<0x111>(gc) + dppz<0x10F>(gb), gn = dppz<0x101>(gc) + dppz<0x11F>(ga);
;                         const float up = dppz<0x111>(uc) + dppz<0x10F>(ub), un = dppz<0x101>(uc) + dppz<0x11F>(ua);
;                         const float hg = wg0[jj] * gp + wg1[jj] * gc + wg2[jj] * gn + bg[jj];
;                         const float hu = wu0[jj] * up + wu1[jj] * uc + wu2[jj] * un + bu[jj];
;                         const float sg = __builtin_amdgcn_rcpf(1.f + __builtin_amdgcn_exp2f(-1.4426950408889634f * hg));
;                         y[jj] = hg * sg * hu; }
;                     u32x2 pk; pk.x = cvt_pk_bf16(y[0], y[1]); pk.y = cvt_pk_bf16(y[2], y[3]);
;                     if (n == 0) ypk[ai][m] = pk;
;                     else {
;                         const bool deferred = (m == 0 && fr == 0) || (m == 3 && fr == 15);
;                         if (!deferred) { u32x4 w; w.x = ypk[ai][m].x; w.y = ypk[ai][m].y; w.z = pk.x; w.w = pk.y; *(u32x4*)(act + (size_t)(r64 + m * 16 + fr) * DFF + c0) = w; } }
	v_fmac_f32_dpp v213, v95, v163 row_shl:1 row_mask:0xf bank_mask:0xf bound_ctrl:1
	v_pk_mul_f32 v[218:219], v[142:143], s[54:55] op_sel_hi:[1,0]
	v_pk_mul_f32 v[252:253], v[178:179], s[54:55] op_sel_hi:[1,0]
	v_pk_mul_f32 v[228:229], v[210:211], s[54:55] op_sel_hi:[1,0]
	v_pk_mul_f32 v[230:231], v[212:213], s[54:55] op_sel_hi:[1,0]
	v_exp_f32_e32 v218, v218
	v_exp_f32_e32 v219, v219
	v_exp_f32_e32 v252, v252
	v_exp_f32_e32 v253, v253
	v_exp_f32_e32 v228, v228
	v_exp_f32_e32 v229, v229
	v_exp_f32_e32 v230, v230
	v_exp_f32_e32 v231, v231
	v_pk_add_f32 v[218:219], v[218:219], s[56:57] op_sel_hi:[1,0]
	v_pk_add_f32 v[252:253], v[252:253], s[56:57] op_sel_hi:[1,0]
	v_pk_add_f32 v[228:229], v[228:229], s[56:57] op_sel_hi:[1,0]
	v_pk_add_f32 v[230:231], v[230:231], s[56:57] op_sel_hi:[1,0]
	v_rcp_f32_e32 v218, v218
	v_rcp_f32_e32 v219, v219
	v_rcp_f32_e32 v252, v252
	v_rcp_f32_e32 v253, v253
	v_rcp_f32_e32 v228, v228
	v_rcp_f32_e32 v229, v229
	v_rcp_f32_e32 v230, v230
	v_rcp_f32_e32 v231, v231
	v_pk_mul_f32 v[142:143], v[142:143], v[218:219]
	v_pk_mul_f32 v[178:179], v[178:179], v[252:253]
	v_pk_mul_f32 v[210:211], v[210:211], v[228:229]
	v_pk_mul_f32 v[212:213], v[212:213], v[230:231]
	v_pk_fma_f32 v[218:219], v[190:191], v[86:87], v[222:223]
	v_pk_fma_f32 v[252:253], v[190:191], v[30:31], v[222:223]
	v_pk_fma_f32 v[228:229], v[190:191], v[26:27], v[222:223]
	v_pk_fma_f32 v[230:231], v[190:191], v[74:75], v[222:223]
	v_pk_fma_f32 v[218:219], v[202:203], v[30:31], v[218:219]
	v_pk_fma_f32 v[252:253], v[182:183], v[86:87], v[252:253]
	v_pk_fma_f32 v[228:229], v[182:183], v[30:31], v[228:229]
	v_pk_fma_f32 v[230:231], v[182:183], v[26:27], v[230:231]
	v_pk_fma_f32 v[252:253], v[202:203], v[26:27], v[252:253]
	v_pk_fma_f32 v[228:229], v[202:203], v[74:75], v[228:229]
	v_fmac_f32_dpp v218, v74, v182 row_shr:1 row_mask:0xf bank_mask:0xf bound_ctrl:1
	v_fmac_f32_dpp v230, v86, v202 row_shl:1 row_mask:0xf bank_mask:0xf bound_ctrl:1
	v_fmac_f32_dpp v219, v75, v183 row_shr:1 row_mask:0xf bank_mask:0xf bound_ctrl:1
	v_fmac_f32_dpp v231, v87, v203 row_shl:1 row_mask:0xf bank_mask:0xf bound_ctrl:1
	v_pk_mul_f32 v[142:143], v[142:143], v[218:219]
	v_pk_mul_f32 v[178:179], v[178:179], v[252:253]
	v_pk_mul_f32 v[210:211], v[210:211], v[228:229]
	v_pk_mul_f32 v[212:213], v[212:213], v[230:231]
	v_cvt_pk_bf16_f32 v237, v142, v143
	v_cvt_pk_bf16_f32 v241, v178, v179
	v_cvt_pk_bf16_f32 v245, v210, v211
	v_cvt_pk_bf16_f32 v249, v212, v213
	v_pk_fma_f32 v[142:143], v[156:157], v[88:89], v[172:173]
	v_pk_fma_f32 v[178:179], v[156:157], v[12:13], v[172:173]
	v_pk_fma_f32 v[210:211], v[156:157], v[4:5], v[172:173]
	v_pk_fma_f32 v[212:213], v[156:157], v[56:57], v[172:173]
	v_pk_fma_f32 v[142:143], v[164:165], v[12:13], v[142:143]
	v_pk_fma_f32 v[178:179], v[148:149], v[88:89], v[178:179]
	v_pk_fma_f32 v[210:211], v[148:149], v[12:13], v[210:211]
	v_pk_fma_f32 v[212:213], v[148:149], v[4:5], v[212:213]
	v_pk_fma_f32 v[178:179], v[164:165], v[4:5], v[178:179]
	v_pk_fma_f32 v[210:211], v[164:165], v[56:57], v[210:211]
	v_fmac_f32_dpp v142, v56, v148 row_shr:1 row_mask:0xf bank_mask:0xf bound_ctrl:1
	v_fmac_f32_dpp v212, v88, v164 row_shl:1 row_mask:0xf bank_mask:0xf bound_ctrl:1
	v_fmac_f32_dpp v143, v57, v149 row_shr:1 row_mask:0xf bank_mask:0xf bound_ctrl:1
	v_fmac_f32_dpp v213, v89, v165 row_shl:1 row_mask:0xf bank_mask:0xf bound_ctrl:1
	v_pk_mul_f32 v[218:219], v[142:143], s[54:55] op_sel_hi:[1,0]
	v_pk_mul_f32 v[252:253], v[178:179], s[54:55] op_sel_hi:[1,0]
	v_pk_mul_f32 v[228:229], v[210:211], s[54:55] op_sel_hi:[1,0]
	v_pk_mul_f32 v[230:231], v[212:213], s[54:55] op_sel_hi:[1,0]
	v_exp_f32_e32 v218, v218
	v_exp_f32_e32 v219, v219
	v_exp_f32_e32 v252, v252
	v_exp_f32_e32 v253, v253
	v_exp_f32_e32 v228, v228
	v_exp_f32_e32 v229, v229
	v_exp_f32_e32 v230, v230
	v_exp_f32_e32 v231, v231
	v_pk_add_f32 v[218:219], v[218:219], s[56:57] op_sel_hi:[1,0]
	v_pk_add_f32 v[252:253], v[252:253], s[56:57] op_sel_hi:[1,0]
	v_pk_add_f32 v[228:229], v[228:229], s[56:57] op_sel_hi:[1,0]
	v_pk_add_f32 v[230:231], v[230:231], s[56:57] op_sel_hi:[1,0]
	v_rcp_f32_e32 v218, v218
	v_rcp_f32_e32 v219, v219
	v_rcp_f32_e32 v252, v252
	v_rcp_f32_e32 v253, v253
	v_rcp_f32_e32 v228, v228
	v_rcp_f32_e32 v229, v229
	v_rcp_f32_e32 v230, v230
	v_rcp_f32_e32 v231, v231
	v_pk_mul_f32 v[142:143], v[142:143], v[218:219]
	v_pk_mul_f32 v[178:179], v[178:179], v[252:253]
	v_pk_mul_f32 v[210:211], v[210:211], v[228:229]
	v_pk_mul_f32 v[212:213], v[212:213], v[230:231]
	v_pk_fma_f32 v[218:219], v[196:197], v[80:81], v[224:225]
	v_pk_fma_f32 v[252:253], v[196:197], v[8:9], v[224:225]
	v_pk_fma_f32 v[228:229], v[196:197], v[0:1], v[224:225]
	v_pk_fma_f32 v[230:231], v[196:197], v[40:41], v[224:225]
	v_pk_fma_f32 v[218:219], v[204:205], v[8:9], v[218:219]
; __device__ __forceinline__ unsigned cvt_pk_bf16(float lo, float hi) { unsigned r; asm volatile("v_cvt_pk_bf16_f32 %0, %1, %2" : "=v"(r) : "v"(lo), "v"(hi)); return r; }
;     __device__ __forceinline__ void operator()(f32x4 (&acc)[2][2][4][2], const Unit& u, int wr, int wc, int fr, int fq, const LAS float* rtab) const {
;     ...
;                     for (int jj = 0; jj < 4; ++jj) {
;                         const float gc = acc[ai][0][m][n][jj], uc = acc[ai][1][m][n][jj];
;                         const float gb = m > 0 ? acc[ai][0][m - 1][n][jj] : 0.f, ga = m < 3 ? acc[ai][0][m + 1][n][jj] : 0.f;
;                         const float ub = m > 0 ? acc[ai][1][m - 1][n][jj] : 0.f, ua = m < 3 ? acc[ai][1][m + 1][n][jj] : 0.f;
;                         const float gp = dppz<0x111>(gc) + dppz<0x10F>(gb), gn = dppz<0x101>(gc) + dppz<0x11F>(ga);
;                         const float up = dppz<0x111>(uc) + dppz<0x10F>(ub), un = dppz<0x101>(uc) + dppz<0x11F>(ua);
;                         const float hg = wg0[jj] * gp + wg1[jj] * gc + wg2[jj] * gn + bg[jj];
;                         const float hu = wu0[jj] * up + wu1[jj] * uc + wu2[jj] * un + bu[jj];
;                         const float sg = __builtin_amdgcn_rcpf(1.f + __builtin_amdgcn_exp2f(-1.4426950408889634f * hg));
;                         y[jj] = hg * sg * hu; }
;                     u32x2 pk; pk.x = cvt_pk_bf16(y[0], y[1]); pk.y = cvt_pk_bf16(y[2], y[3]);
;                     if (n == 0) ypk[ai][m] = pk;
;                     else {
;                         const bool deferred = (m == 0 && fr == 0) || (m == 3 && fr == 15);
;                         if (!deferred) { u32x4 w; w.x = ypk[ai][m].x; w.y = ypk[ai][m].y; w.z = pk.x; w.w = pk.y; *(u32x4*)(act + (size_t)(r64 + m * 16 + fr) * DFF + c0) = w; } }
; template <class Epi, bool KREV = false>
; __device__ __forceinline__ void gemm_phase(LAS unsigned char* lds, const Gemm g, const StaticOrder& S, const Epi& E, int wave_s) {
;     ...
;         if (!has_next) break;
; #pragma unroll
;         for (int a = 0; a < 2; ++a)
; #pragma unroll
;             for (int b = 0; b < 2; ++b)
; #pragma unroll
;                 for (int m = 0; m < 4; ++m)
; #pragma unroll
;                     for (int n = 0; n < 2; ++n) acc[a][b][m][n] = (f32x4){0.f, 0.f, 0.f, 0.f};
;         cur = nxt; cA = nA; cB = nB; ++ui;
;         if (wr == 1) PG8_BAR;
;     }
	v_pk_fma_f32 v[252:253], v[184:185], v[80:81], v[252:253]
	v_pk_fma_f32 v[228:229], v[184:185], v[8:9], v[228:229]
	v_pk_fma_f32 v[230:231], v[184:185], v[0:1], v[230:231]
	v_pk_fma_f32 v[252:253], v[204:205], v[0:1], v[252:253]
	v_pk_fma_f32 v[228:229], v[204:205], v[40:41], v[228:229]
	v_fmac_f32_dpp v218, v40, v184 row_shr:1 row_mask:0xf bank_mask:0xf bound_ctrl:1
	v_fmac_f32_dpp v230, v80, v204 row_shl:1 row_mask:0xf bank_mask:0xf bound_ctrl:1
	v_fmac_f32_dpp v219, v41, v185 row_shr:1 row_mask:0xf bank_mask:0xf bound_ctrl:1
	v_fmac_f32_dpp v231, v81, v205 row_shl:1 row_mask:0xf bank_mask:0xf bound_ctrl:1
	v_pk_mul_f32 v[142:143], v[142:143], v[218:219]
	v_pk_mul_f32 v[178:179], v[178:179], v[252:253]
	v_pk_mul_f32 v[210:211], v[210:211], v[228:229]
	v_pk_mul_f32 v[212:213], v[212:213], v[230:231]
	v_cvt_pk_bf16_f32 v238, v142, v143
	v_cvt_pk_bf16_f32 v242, v178, v179
	v_cvt_pk_bf16_f32 v246, v210, v211
	v_cvt_pk_bf16_f32 v250, v212, v213
	v_pk_fma_f32 v[142:143], v[158:159], v[90:91], v[174:175]
	v_pk_fma_f32 v[178:179], v[158:159], v[14:15], v[174:175]
	v_pk_fma_f32 v[210:211], v[158:159], v[6:7], v[174:175]
	v_pk_fma_f32 v[212:213], v[158:159], v[58:59], v[174:175]
	v_pk_fma_f32 v[142:143], v[166:167], v[14:15], v[142:143]
	v_pk_fma_f32 v[178:179], v[150:151], v[90:91], v[178:179]
	v_pk_fma_f32 v[210:211], v[150:151], v[14:15], v[210:211]
	v_pk_fma_f32 v[212:213], v[150:151], v[6:7], v[212:213]
	v_pk_fma_f32 v[178:179], v[166:167], v[6:7], v[178:179]
	v_pk_fma_f32 v[210:211], v[166:167], v[58:59], v[210:211]
	v_fmac_f32_dpp v142, v58, v150 row_shr:1 row_mask:0xf bank_mask:0xf bound_ctrl:1
	v_fmac_f32_dpp v212, v90, v166 row_shl:1 row_mask:0xf bank_mask:0xf bound_ctrl:1
	v_fmac_f32_dpp v143, v59, v151 row_shr:1 row_mask:0xf bank_mask:0xf bound_ctrl:1
	v_fmac_f32_dpp v213, v91, v167 row_shl:1 row_mask:0xf bank_mask:0xf bound_ctrl:1
	v_pk_mul_f32 v[218:219], v[142:143], s[54:55] op_sel_hi:[1,0]
	v_pk_mul_f32 v[252:253], v[178:179], s[54:55] op_sel_hi:[1,0]
	v_pk_mul_f32 v[228:229], v[210:211], s[54:55] op_sel_hi:[1,0]
	v_pk_mul_f32 v[230:231], v[212:213], s[54:55] op_sel_hi:[1,0]
	v_exp_f32_e32 v218, v218
	v_exp_f32_e32 v219, v219
	v_exp_f32_e32 v252, v252
	v_exp_f32_e32 v253, v253
	v_exp_f32_e32 v228, v228
	v_exp_f32_e32 v229, v229
	v_exp_f32_e32 v230, v230
	v_exp_f32_e32 v231, v231
	v_pk_add_f32 v[218:219], v[218:219], s[56:57] op_sel_hi:[1,0]
	v_pk_add_f32 v[252:253], v[252:253], s[56:57] op_sel_hi:[1,0]
	v_pk_add_f32 v[228:229], v[228:229], s[56:57] op_sel_hi:[1,0]
	v_pk_add_f32 v[230:231], v[230:231], s[56:57] op_sel_hi:[1,0]
	v_rcp_f32_e32 v218, v218
	v_rcp_f32_e32 v219, v219
	v_rcp_f32_e32 v252, v252
	v_rcp_f32_e32 v253, v253
	v_rcp_f32_e32 v228, v228
	v_rcp_f32_e32 v229, v229
	v_rcp_f32_e32 v230, v230
	v_rcp_f32_e32 v231, v231
	v_pk_mul_f32 v[142:143], v[142:143], v[218:219]
	v_pk_mul_f32 v[178:179], v[178:179], v[252:253]
	v_pk_mul_f32 v[210:211], v[210:211], v[228:229]
	v_pk_mul_f32 v[212:213], v[212:213], v[230:231]
	v_pk_fma_f32 v[218:219], v[198:199], v[82:83], v[226:227]
	v_pk_fma_f32 v[252:253], v[198:199], v[10:11], v[226:227]
	v_pk_fma_f32 v[228:229], v[198:199], v[2:3], v[226:227]
	v_pk_fma_f32 v[230:231], v[198:199], v[42:43], v[226:227]
	v_pk_fma_f32 v[218:219], v[206:207], v[10:11], v[218:219]
	v_pk_fma_f32 v[252:253], v[186:187], v[82:83], v[252:253]
	v_pk_fma_f32 v[228:229], v[186:187], v[10:11], v[228:229]
	v_pk_fma_f32 v[230:231], v[186:187], v[2:3], v[230:231]
	v_pk_fma_f32 v[252:253], v[206:207], v[2:3], v[252:253]
	v_pk_fma_f32 v[228:229], v[206:207], v[42:43], v[228:229]
	v_fmac_f32_dpp v218, v42, v186 row_shr:1 row_mask:0xf bank_mask:0xf bound_ctrl:1
	v_fmac_f32_dpp v230, v82, v206 row_shl:1 row_mask:0xf bank_mask:0xf bound_ctrl:1
	v_fmac_f32_dpp v219, v43, v187 row_shr:1 row_mask:0xf bank_mask:0xf bound_ctrl:1
	v_fmac_f32_dpp v231, v83, v207 row_shl:1 row_mask:0xf bank_mask:0xf bound_ctrl:1
	v_pk_mul_f32 v[142:143], v[142:143], v[218:219]
	v_pk_mul_f32 v[178:179], v[178:179], v[252:253]
	v_pk_mul_f32 v[210:211], v[210:211], v[228:229]
	v_pk_mul_f32 v[212:213], v[212:213], v[230:231]
	v_cvt_pk_bf16_f32 v239, v142, v143
	v_cvt_pk_bf16_f32 v243, v178, v179
	v_cvt_pk_bf16_f32 v247, v210, v211
	v_cvt_pk_bf16_f32 v251, v212, v213
	s_add_u32 s58, s28, 0x160000
	s_addc_u32 s59, s29, 0
	s_mov_b64 exec, s[12:13]
	global_store_dwordx4 v234, v[236:239], s[58:59]
	s_mov_b64 exec, -1
	s_add_u32 s58, s28, 0x162c00
	s_addc_u32 s59, s29, 0
	global_store_dwordx4 v234, v[240:243], s[58:59]
	s_add_u32 s58, s28, 0x165800
	s_addc_u32 s59, s29, 0
	global_store_dwordx4 v234, v[244:247], s[58:59]
	s_add_u32 s58, s28, 0x168400
	s_addc_u32 s59, s29, 0
	s_mov_b64 exec, s[10:11]
	global_store_dwordx4 v234, v[248:251], s[58:59]
	s_mov_b64 exec, -1
	s_andn2_b64 vcc, exec, s[52:53]
	s_mov_b64 s[52:53], -1
	s_cbranch_vccnz .LBB0_834
